# fp8 packing: dropped the 64 zero-initialising v_mov before v_cvt_pk_fp8_f32 pairs (both halves are written by the pair)
# baseline (speedup 1.0000x reference)
; __device__ __forceinline__ unsigned pk4_fp8(float a, float b, float c, float d) { int w = 0; w = __builtin_amdgcn_cvt_pk_fp8_f32(a, b, w, false); w = __builtin_amdgcn_cvt_pk_fp8_f32(c, d, w, true); return (unsigned)w; }
; #define GAS __attribute__((address_space(1)))
; #define LAS __attribute__((address_space(3)))
; #define LDS_WAIT() asm volatile("s_waitcnt lgkmcnt(0)" ::: "memory")
; __device__ __forceinline__ unsigned pk4_fp8(float a, float b, float c, float d) { int w = 0; w = __builtin_amdgcn_cvt_pk_fp8_f32(a, b, w, false); w = __builtin_amdgcn_cvt_pk_fp8_f32(c, d, w, true); return (unsigned)w; }
; __device__ __forceinline__ void cvt_store(const CvtItem& c, const f32x4 (&v)[8], LAS float* scr, int lane) {
; #pragma unroll
;     for (int i = 0; i < 8; ++i) { const int kk = 4 * i + (lane >> 4); LAS float* p = scr + kk * 65 + 4 * (lane & 15); p[0] = v[i][0]; p[1] = v[i][1]; p[2] = v[i][2]; p[3] = v[i][3]; }
;     LDS_WAIT(); asm volatile("" ::: "memory");
;     if (c.f8) {
; #pragma unroll
;         for (int j = 0; j < 2; ++j) { const int idx = lane + 64 * j, n = idx >> 1, cc = idx & 1; const LAS float* s = scr + (16 * cc) * 65 + n;
;             v4u o; o.x = pk4_fp8(s[0 * 65] * F8_SW, s[1 * 65] * F8_SW, s[2 * 65] * F8_SW, s[3 * 65] * F8_SW); o.y = pk4_fp8(s[4 * 65] * F8_SW, s[5 * 65] * F8_SW, s[6 * 65] * F8_SW, s[7 * 65] * F8_SW);
;             o.z = pk4_fp8(s[8 * 65] * F8_SW, s[9 * 65] * F8_SW, s[10 * 65] * F8_SW, s[11 * 65] * F8_SW); o.w = pk4_fp8(s[12 * 65] * F8_SW, s[13 * 65] * F8_SW, s[14 * 65] * F8_SW, s[15 * 65] * F8_SW);
;             *(GAS v4u*)(c.dst + (size_t)n * D + 16 * cc) = o; }
.LBB0_536:
	s_waitcnt vmcnt(7)
	ds_write2_b32 v105, v34, v35 offset1:1
	ds_write2_b32 v105, v36, v37 offset0:2 offset1:3
	v_add_u32_e32 v34, 0x410, v105
	s_waitcnt vmcnt(6)
	ds_write2_b32 v34, v38, v39 offset1:1
	v_add_u32_e32 v34, 0x418, v105
	ds_write2_b32 v34, v40, v41 offset1:1
	v_add_u32_e32 v34, 0x820, v105
	s_waitcnt vmcnt(5)
	ds_write2_b32 v34, v42, v43 offset1:1
	v_add_u32_e32 v34, 0x828, v105
	ds_write2_b32 v34, v44, v45 offset1:1
	v_add_u32_e32 v34, 0xc30, v105
	s_waitcnt vmcnt(4)
	ds_write2_b32 v34, v46, v47 offset1:1
	v_add_u32_e32 v34, 0xc38, v105
	ds_write2_b32 v34, v48, v49 offset1:1
	v_add_u32_e32 v34, 0x1040, v105
	s_waitcnt vmcnt(3)
	ds_write2_b32 v34, v50, v51 offset1:1
	v_add_u32_e32 v34, 0x1048, v105
	ds_write2_b32 v34, v52, v53 offset1:1
	v_add_u32_e32 v34, 0x1450, v105
	s_waitcnt vmcnt(2)
	ds_write2_b32 v34, v54, v55 offset1:1
	v_add_u32_e32 v34, 0x1458, v105
	ds_write2_b32 v34, v56, v57 offset1:1
	v_add_u32_e32 v34, 0x1860, v105
	s_waitcnt vmcnt(1)
	ds_write2_b32 v34, v58, v59 offset1:1
	v_add_u32_e32 v34, 0x1868, v105
	ds_write2_b32 v34, v60, v61 offset1:1
	v_add_u32_e32 v34, 0x1c70, v105
	s_waitcnt vmcnt(0)
	ds_write2_b32 v34, v62, v63 offset1:1
	v_add_u32_e32 v34, 0x1c78, v105
	ds_write2_b32 v34, v64, v65 offset1:1
	s_waitcnt lgkmcnt(0)
	s_cmp_eq_u32 s34, 0
	s_cbranch_scc1 .LBB0_538
	ds_read2_b32 v[34:35], v81 offset1:65
	s_mov_b64 s[42:43], 0
	s_waitcnt lgkmcnt(0)
	v_mul_f32_e32 v36, 0x42800000, v34
	v_mul_f32_e32 v37, 0x42800000, v35
	ds_read2_b32 v[34:35], v81 offset0:130 offset1:195
	s_waitcnt lgkmcnt(0)
	v_mul_f32_e32 v38, 0x42800000, v34
	v_cvt_pk_fp8_f32 v34, v36, v37
	v_mul_f32_e32 v35, 0x42800000, v35
	v_cvt_pk_fp8_f32 v34, v38, v35 op_sel:[0,0,1]
	v_add_u32_e32 v35, 0x400, v81
	ds_read2_b32 v[36:37], v35 offset0:4 offset1:69
	s_waitcnt lgkmcnt(0)
	v_mul_f32_e32 v38, 0x42800000, v36
	v_mul_f32_e32 v39, 0x42800000, v37
	ds_read2_b32 v[36:37], v35 offset0:134 offset1:199
	v_cvt_pk_fp8_f32 v35, v38, v39
	v_add_u32_e32 v38, 0x800, v81
	s_waitcnt lgkmcnt(0)
	v_mul_f32_e32 v36, 0x42800000, v36
	v_mul_f32_e32 v37, 0x42800000, v37
	v_cvt_pk_fp8_f32 v35, v36, v37 op_sel:[0,0,1]
	ds_read2_b32 v[36:37], v38 offset0:8 offset1:73
	s_waitcnt lgkmcnt(0)
	v_mul_f32_e32 v39, 0x42800000, v36
	v_mul_f32_e32 v40, 0x42800000, v37
	ds_read2_b32 v[36:37], v38 offset0:138 offset1:203
	s_waitcnt lgkmcnt(0)
	v_mul_f32_e32 v38, 0x42800000, v36
	v_cvt_pk_fp8_f32 v36, v39, v40
	v_mul_f32_e32 v37, 0x42800000, v37
	v_cvt_pk_fp8_f32 v36, v38, v37 op_sel:[0,0,1]
	v_add_u32_e32 v37, 0xc00, v81
	ds_read2_b32 v[38:39], v37 offset0:12 offset1:77
	s_waitcnt lgkmcnt(0)
	v_mul_f32_e32 v40, 0x42800000, v38
	v_mul_f32_e32 v41, 0x42800000, v39
	ds_read2_b32 v[38:39], v37 offset0:142 offset1:207
	v_cvt_pk_fp8_f32 v37, v40, v41
	s_waitcnt lgkmcnt(0)
	v_mul_f32_e32 v38, 0x42800000, v38
	v_mul_f32_e32 v39, 0x42800000, v39
	v_cvt_pk_fp8_f32 v37, v38, v39 op_sel:[0,0,1]
	v_lshl_add_u64 v[38:39], s[8:9], 0, v[88:89]
	v_lshl_add_u64 v[38:39], v[38:39], 0, v[86:87]
	global_store_dwordx4 v[38:39], v[34:37], off
	ds_read2_b32 v[34:35], v85 offset1:65
	s_waitcnt lgkmcnt(0)
	v_mul_f32_e32 v36, 0x42800000, v34
	v_mul_f32_e32 v37, 0x42800000, v35
	ds_read2_b32 v[34:35], v85 offset0:130 offset1:195
	s_waitcnt lgkmcnt(0)
	v_mul_f32_e32 v38, 0x42800000, v34
	v_cvt_pk_fp8_f32 v34, v36, v37
	v_mul_f32_e32 v35, 0x42800000, v35
	v_cvt_pk_fp8_f32 v34, v38, v35 op_sel:[0,0,1]
	v_add_u32_e32 v35, 0x400, v85
	ds_read2_b32 v[36:37], v35 offset0:4 offset1:69
	s_waitcnt lgkmcnt(0)
	v_mul_f32_e32 v38, 0x42800000, v36
	v_mul_f32_e32 v39, 0x42800000, v37
	ds_read2_b32 v[36:37], v35 offset0:134 offset1:199
	v_cvt_pk_fp8_f32 v35, v38, v39
	v_add_u32_e32 v38, 0x800, v85
	s_waitcnt lgkmcnt(0)
	v_mul_f32_e32 v36, 0x42800000, v36
	v_mul_f32_e32 v37, 0x42800000, v37
	v_cvt_pk_fp8_f32 v35, v36, v37 op_sel:[0,0,1]
	ds_read2_b32 v[36:37], v38 offset0:8 offset1:73
	s_waitcnt lgkmcnt(0)
	v_mul_f32_e32 v39, 0x42800000, v36
	v_mul_f32_e32 v40, 0x42800000, v37
	ds_read2_b32 v[36:37], v38 offset0:138 offset1:203
	s_waitcnt lgkmcnt(0)
	v_mul_f32_e32 v38, 0x42800000, v36
	v_cvt_pk_fp8_f32 v36, v39, v40
	v_mul_f32_e32 v37, 0x42800000, v37
	v_cvt_pk_fp8_f32 v36, v38, v37 op_sel:[0,0,1]
	v_add_u32_e32 v37, 0xc00, v85
	ds_read2_b32 v[38:39], v37 offset0:12 offset1:77
	s_waitcnt lgkmcnt(0)
	v_mul_f32_e32 v40, 0x42800000, v38
	v_mul_f32_e32 v41, 0x42800000, v39
	ds_read2_b32 v[38:39], v37 offset0:142 offset1:207
	v_cvt_pk_fp8_f32 v37, v40, v41
	s_waitcnt lgkmcnt(0)
	v_mul_f32_e32 v38, 0x42800000, v38
	v_mul_f32_e32 v39, 0x42800000, v39
	v_cvt_pk_fp8_f32 v37, v38, v39 op_sel:[0,0,1]
	s_branch .LBB0_539

; #define LAS __attribute__((address_space(3)))
; __device__ __forceinline__ void ln_stats(const f32x4 (&v)[4], float& mean, float& rstd) {
;     float s = 0.f;
; #pragma unroll
;     for (int j = 0; j < 4; ++j) s += (v[j][0] + v[j][1]) + (v[j][2] + v[j][3]);
;     mean = wave_sum(s) * (1.f / D); float q = 0.f;
; __device__ __forceinline__ void p_r2(const Args& a, LAS unsigned char* lds, volatile LAS unsigned* MISC, int l, int wg, int G, int wave, int lane, int tid) {
;     ...
;                 else { v2u xw[4]; unpack_row_raw(xpre[r], lane, xw);
; #pragma unroll
;                     for (int j = 0; j < 4; ++j) x[r][j] = (f32x4){bf_lo(xw[j].x), bf_hi(xw[j].x), bf_lo(xw[j].y), bf_hi(xw[j].y)}; }
;                 unpack_row_raw(mpre[r], lane, mw[r]); }
;             if (it + 1 < 16) {
; #pragma unroll
;                 for (int r = 0; r < 2; ++r) { load_row_raw(MIX + (size_t)(t0 + 16 + r) * D, lane, mpre[r]); if (l != 0) load_row_raw(xbf + (size_t)(t0 + 16 + r) * D, lane, xpre[r]); } }
; #pragma unroll
;             for (int j = 0; j < 4; ++j) { const f32x4 g1 = *(const LAS f32x4*)(lds + R2_PAR + (0 * 256 + lane + 64 * j) * 16);
; #pragma unroll
;                 for (int r = 0; r < 2; ++r) { const f32x4 mx = (f32x4){bf_lo(mw[r][j].x), bf_hi(mw[r][j].x), bf_lo(mw[r][j].y), bf_hi(mw[r][j].y)}; x[r][j] = ALPHA * x[r][j] + (1.0f + g1) * mx; } }
;             float mean[2], rstd[2];
; #pragma unroll
;             for (int r = 0; r < 2; ++r) ln_stats(x[r], mean[r], rstd[r]);
.LBB0_836:
	v_cndmask_b32_e64 v136, v188, v136, s[44:45]
	v_cndmask_b32_e64 v138, v138, v188, s[44:45]
	v_cndmask_b32_e64 v188, v191, v133, s[44:45]
	v_cndmask_b32_e64 v133, v18, v124, s[44:45]
	v_cndmask_b32_e64 v193, v126, v18, s[44:45]
	v_add_u32_e32 v18, 0, v156
	v_cndmask_b32_e64 v137, v190, v137, s[44:45]
	v_cndmask_b32_e64 v139, v139, v190, s[44:45]
	v_cndmask_b32_e64 v190, v189, v132, s[44:45]
	v_cndmask_b32_e64 v132, v186, v125, s[44:45]
	v_cndmask_b32_e64 v192, v127, v186, s[44:45]
	v_add_u32_e32 v186, 0x14800, v18
	v_cndmask_b32_e64 v194, v187, v121, s[44:45]
	v_cndmask_b32_e64 v195, v19, v120, s[44:45]
	v_cndmask_b32_e64 v187, v123, v187, s[44:45]
	v_cndmask_b32_e64 v196, v122, v19, s[44:45]
	ds_read_b128 v[120:123], v186
	v_lshlrev_b32_e32 v18, 16, v133
	v_and_b32_e32 v19, 0xffff0000, v133
	v_and_b32_e32 v133, 0xffff0000, v137
	v_lshlrev_b32_e32 v126, 16, v136
	s_waitcnt lgkmcnt(0)
	v_pk_add_f32 v[122:123], v[122:123], 1.0 op_sel_hi:[1,0]
	v_pk_add_f32 v[124:125], v[120:121], 1.0 op_sel_hi:[1,0]
	v_lshlrev_b32_e32 v120, 16, v132
	v_and_b32_e32 v121, 0xffff0000, v132
	v_lshlrev_b32_e32 v132, 16, v137
	v_and_b32_e32 v127, 0xffff0000, v136
	v_pk_mul_f32 v[132:133], v[122:123], v[132:133]
	v_cndmask_b32_e64 v191, v135, v191, s[44:45]
	v_cndmask_b32_e64 v189, v134, v189, s[44:45]
	v_pk_mul_f32 v[120:121], v[122:123], v[120:121]
	v_pk_mul_f32 v[18:19], v[124:125], v[18:19]
	v_pk_mul_f32 v[122:123], v[124:125], v[126:127]
	v_pk_fma_f32 v[124:125], v[150:151], s[10:11], v[132:133] op_sel_hi:[1,0,1]
	ds_read_b128 v[132:135], v186 offset:1024
	v_lshlrev_b32_e32 v126, 16, v193
	v_and_b32_e32 v127, 0xffff0000, v193
	v_pk_fma_f32 v[120:121], v[146:147], s[10:11], v[120:121] op_sel_hi:[1,0,1]
	v_pk_fma_f32 v[18:19], v[144:145], s[10:11], v[18:19] op_sel_hi:[1,0,1]
	s_waitcnt lgkmcnt(0)
	v_pk_add_f32 v[134:135], v[134:135], 1.0 op_sel_hi:[1,0]
	v_pk_add_f32 v[136:137], v[132:133], 1.0 op_sel_hi:[1,0]
	v_lshlrev_b32_e32 v132, 16, v192
	v_and_b32_e32 v133, 0xffff0000, v192
	v_pk_mul_f32 v[132:133], v[134:135], v[132:133]
	v_pk_mul_f32 v[126:127], v[136:137], v[126:127]
	v_pk_fma_f32 v[132:133], v[118:119], s[10:11], v[132:133] op_sel_hi:[1,0,1]
	v_pk_fma_f32 v[126:127], v[116:117], s[10:11], v[126:127] op_sel_hi:[1,0,1]
	v_lshlrev_b32_e32 v116, 16, v138
	v_and_b32_e32 v117, 0xffff0000, v138
	v_lshlrev_b32_e32 v118, 16, v139
	v_and_b32_e32 v119, 0xffff0000, v139
	v_pk_mul_f32 v[118:119], v[134:135], v[118:119]
	v_pk_mul_f32 v[116:117], v[136:137], v[116:117]
	ds_read_b128 v[134:137], v186 offset:2048
	v_pk_fma_f32 v[116:117], v[140:141], s[10:11], v[116:117] op_sel_hi:[1,0,1]
	v_lshlrev_b32_e32 v140, 16, v194
	v_and_b32_e32 v141, 0xffff0000, v194
	v_pk_fma_f32 v[122:123], v[148:149], s[10:11], v[122:123] op_sel_hi:[1,0,1]
	s_waitcnt lgkmcnt(0)
	v_pk_add_f32 v[136:137], v[136:137], 1.0 op_sel_hi:[1,0]
	v_pk_add_f32 v[138:139], v[134:135], 1.0 op_sel_hi:[1,0]
	v_lshlrev_b32_e32 v134, 16, v195
	v_and_b32_e32 v135, 0xffff0000, v195
	v_pk_mul_f32 v[134:135], v[138:139], v[134:135]
	v_pk_mul_f32 v[140:141], v[136:137], v[140:141]
	v_pk_fma_f32 v[134:135], v[112:113], s[10:11], v[134:135] op_sel_hi:[1,0,1]
	v_pk_fma_f32 v[114:115], v[114:115], s[10:11], v[140:141] op_sel_hi:[1,0,1]
	v_lshlrev_b32_e32 v112, 16, v190
	v_and_b32_e32 v113, 0xffff0000, v190
	v_lshlrev_b32_e32 v140, 16, v188
	v_and_b32_e32 v141, 0xffff0000, v188
	v_pk_mul_f32 v[138:139], v[138:139], v[112:113]
	v_pk_mul_f32 v[112:113], v[136:137], v[140:141]
	v_pk_fma_f32 v[136:137], v[128:129], s[10:11], v[138:139] op_sel_hi:[1,0,1]
	v_pk_fma_f32 v[112:113], v[130:131], s[10:11], v[112:113] op_sel_hi:[1,0,1]
	ds_read_b128 v[128:131], v186 offset:3072
	v_lshlrev_b32_e32 v138, 16, v196
	v_and_b32_e32 v139, 0xffff0000, v196
	v_lshlrev_b32_e32 v140, 16, v187
	v_and_b32_e32 v141, 0xffff0000, v187
	s_waitcnt lgkmcnt(0)
	v_pk_add_f32 v[128:129], v[128:129], 1.0 op_sel_hi:[1,0]
	v_pk_add_f32 v[130:131], v[130:131], 1.0 op_sel_hi:[1,0]
	v_pk_mul_f32 v[138:139], v[128:129], v[138:139]
	v_pk_mul_f32 v[140:141], v[130:131], v[140:141]
	v_pk_fma_f32 v[146:147], v[104:105], s[10:11], v[138:139] op_sel_hi:[1,0,1]
	v_lshlrev_b32_e32 v104, 16, v189
	v_and_b32_e32 v105, 0xffff0000, v189
	v_lshlrev_b32_e32 v138, 16, v191
	v_and_b32_e32 v139, 0xffff0000, v191
	v_pk_mul_f32 v[128:129], v[128:129], v[104:105]
	v_pk_mul_f32 v[104:105], v[130:131], v[138:139]
	v_pk_fma_f32 v[144:145], v[108:109], s[10:11], v[128:129] op_sel_hi:[1,0,1]
	v_pk_fma_f32 v[104:105], v[110:111], s[10:11], v[104:105] op_sel_hi:[1,0,1]
	v_pk_mov_b32 v[108:109], v[18:19], v[120:121] op_sel:[1,0]
	v_mov_b32_e32 v110, v18
	v_mov_b32_e32 v111, v121
	v_pk_add_f32 v[108:109], v[108:109], v[110:111]
	v_pk_mov_b32 v[110:111], v[126:127], v[132:133] op_sel:[1,0]
	v_mov_b32_e32 v128, v126
	v_mov_b32_e32 v129, v133
	v_pk_add_f32 v[110:111], v[110:111], v[128:129]
	v_pk_fma_f32 v[106:107], v[106:107], s[10:11], v[140:141] op_sel_hi:[1,0,1]
	v_add_f32_e32 v108, v108, v109
	v_pk_add_f32 v[110:111], v[110:111], v[110:111] op_sel:[0,1] op_sel_hi:[1,0]
	v_add_f32_e32 v108, 0, v108
	v_add_f32_e32 v128, v134, v135
	v_add_f32_e32 v130, v114, v115
	v_mov_b32_e32 v109, v146
	v_mov_b32_e32 v111, v147
	v_mov_b32_e32 v129, v106
	v_mov_b32_e32 v131, v107
	v_pk_add_f32 v[108:109], v[108:109], v[110:111]
	v_pk_add_f32 v[110:111], v[128:129], v[130:131]
	v_pk_fma_f32 v[118:119], v[142:143], s[10:11], v[118:119] op_sel_hi:[1,0,1]
	v_pk_add_f32 v[108:109], v[108:109], v[110:111]
	v_mov_b32_e32 v139, v105
	v_add_f32_e32 v108, v108, v109
	s_nop 1
	v_add_f32_dpp v108, v108, v108 quad_perm:[1,0,3,2] row_mask:0xf bank_mask:0xf bound_ctrl:1
	s_nop 1
; __device__ __forceinline__ void ln_stats(const f32x4 (&v)[4], float& mean, float& rstd) {
;     float s = 0.f;
; #pragma unroll
;     for (int j = 0; j < 4; ++j) s += (v[j][0] + v[j][1]) + (v[j][2] + v[j][3]);
;     mean = wave_sum(s) * (1.f / D); float q = 0.f;
; #pragma unroll
;     for (int j = 0; j < 4; ++j) { const f32x4 d = v[j] - mean; q += (d[0] * d[0] + d[1] * d[1]) + (d[2] * d[2] + d[3] * d[3]); }
;     rstd = rsqrtf(wave_sum(q) * (1.f / D) + LN_EPS);
; }
; __device__ __forceinline__ void p_r2(const Args& a, LAS unsigned char* lds, volatile LAS unsigned* MISC, int l, int wg, int G, int wave, int lane, int tid) {
;     ...
;             float mean[2], rstd[2];
; #pragma unroll
;             for (int r = 0; r < 2; ++r) ln_stats(x[r], mean[r], rstd[r]);
	v_add_f32_dpp v108, v108, v108 quad_perm:[2,3,0,1] row_mask:0xf bank_mask:0xf bound_ctrl:1
	s_nop 1
	v_add_f32_dpp v108, v108, v108 row_half_mirror row_mask:0xf bank_mask:0xf bound_ctrl:1
	s_nop 1
	v_add_f32_dpp v108, v108, v108 row_mirror row_mask:0xf bank_mask:0xf bound_ctrl:1
	s_nop 0
	v_readlane_b32 s4, v108, 16
	v_readlane_b32 s9, v108, 48
	v_readlane_b32 s2, v108, 0
	v_readlane_b32 s3, v108, 32
	v_mov_b32_e32 v108, s4
	v_mov_b32_e32 v109, s9
	v_pk_add_f32 v[108:109], s[2:3], v[108:109]
	s_nop 0
	v_add_f32_e32 v138, v108, v109
	v_fmamk_f32 v19, v138, 0xba800000, v19
	v_fmac_f32_e32 v18, 0xba800000, v138
	v_fmamk_f32 v121, v138, 0xba800000, v121
	v_fmac_f32_e32 v120, 0xba800000, v138
	v_pk_mul_f32 v[108:109], v[120:121], v[120:121]
	v_pk_mul_f32 v[110:111], v[18:19], v[18:19]
	v_fmamk_f32 v127, v138, 0xba800000, v127
	v_pk_mov_b32 v[128:129], v[110:111], v[108:109] op_sel:[1,0]
	v_mov_b32_e32 v111, v109
	v_pk_add_f32 v[108:109], v[128:129], v[110:111]
	v_fmac_f32_e32 v126, 0xba800000, v138
	v_fmamk_f32 v133, v138, 0xba800000, v133
	v_fmac_f32_e32 v132, 0xba800000, v138
	v_pk_add_f32 v[108:109], v[108:109], v[108:109] op_sel_hi:[0,1]
	v_pk_mul_f32 v[110:111], v[132:133], v[132:133]
	v_pk_mul_f32 v[128:129], v[126:127], v[126:127]
	v_fmac_f32_e32 v134, 0xba800000, v138
	v_pk_mov_b32 v[130:131], v[128:129], v[110:111] op_sel:[1,0]
	v_mov_b32_e32 v129, v111
	v_fmamk_f32 v135, v138, 0xba800000, v135
	v_fmac_f32_e32 v114, 0xba800000, v138
	v_mul_f32_e32 v108, v134, v134
	v_pk_add_f32 v[110:111], v[130:131], v[128:129]
	v_fmamk_f32 v115, v138, 0xba800000, v115
	v_pk_fma_f32 v[128:129], v[134:135], v[134:135], v[108:109] op_sel_hi:[1,1,0]
	v_mul_f32_e32 v108, v114, v114
	v_pk_add_f32 v[110:111], v[110:111], v[110:111] op_sel_hi:[0,1]
	v_pk_fma_f32 v[130:131], v[114:115], v[114:115], v[108:109] op_sel_hi:[1,1,0]
	v_fmamk_f32 v107, v138, 0xba800000, v107
	v_fmac_f32_e32 v106, 0xba800000, v138
	v_fmamk_f32 v147, v138, 0xba800000, v147
	v_fmac_f32_e32 v146, 0xba800000, v138
	v_mul_f32_e32 v128, v146, v146
	v_mul_f32_e32 v130, v147, v147
	v_mul_f32_e32 v108, v106, v106
	v_mul_f32_e32 v110, v107, v107
	v_pk_add_f32 v[128:129], v[128:129], v[130:131]
	v_pk_add_f32 v[108:109], v[108:109], v[110:111]
	v_pk_mov_b32 v[110:111], v[122:123], v[124:125] op_sel:[1,0]
	v_pk_add_f32 v[108:109], v[128:129], v[108:109]
	v_mov_b32_e32 v128, v122
	v_mov_b32_e32 v129, v125
	v_pk_add_f32 v[110:111], v[110:111], v[128:129]
	v_pk_mov_b32 v[128:129], v[116:117], v[118:119] op_sel:[1,0]
	v_mov_b32_e32 v130, v116
	v_mov_b32_e32 v131, v119
	v_pk_add_f32 v[128:129], v[128:129], v[130:131]
	v_add_f32_e32 v110, v110, v111
	v_pk_add_f32 v[128:129], v[128:129], v[128:129] op_sel:[0,1] op_sel_hi:[1,0]
	v_add_f32_e32 v110, 0, v110
	v_add_f32_e32 v130, v136, v137
	v_add_f32_e32 v138, v112, v113
	v_mov_b32_e32 v111, v144
	v_mov_b32_e32 v129, v145
	v_mov_b32_e32 v131, v104
	v_pk_add_f32 v[110:111], v[110:111], v[128:129]
	v_pk_add_f32 v[128:129], v[130:131], v[138:139]
	v_add_f32_e32 v108, v108, v109
	v_pk_add_f32 v[110:111], v[110:111], v[128:129]
	s_nop 0
	v_add_f32_dpp v108, v108, v108 quad_perm:[1,0,3,2] row_mask:0xf bank_mask:0xf bound_ctrl:1
	v_add_f32_e32 v110, v110, v111
	s_nop 0
	v_add_f32_dpp v108, v108, v108 quad_perm:[2,3,0,1] row_mask:0xf bank_mask:0xf bound_ctrl:1
	v_add_f32_dpp v110, v110, v110 quad_perm:[1,0,3,2] row_mask:0xf bank_mask:0xf bound_ctrl:1
	s_nop 0
	v_add_f32_dpp v108, v108, v108 row_half_mirror row_mask:0xf bank_mask:0xf bound_ctrl:1
	v_add_f32_dpp v110, v110, v110 quad_perm:[2,3,0,1] row_mask:0xf bank_mask:0xf bound_ctrl:1
	s_nop 0
	v_add_f32_dpp v108, v108, v108 row_mirror row_mask:0xf bank_mask:0xf bound_ctrl:1
	v_add_f32_dpp v110, v110, v110 row_half_mirror row_mask:0xf bank_mask:0xf bound_ctrl:1
	v_readlane_b32 s4, v108, 16
	v_readlane_b32 s9, v108, 48
	v_add_f32_dpp v110, v110, v110 row_mirror row_mask:0xf bank_mask:0xf bound_ctrl:1
	v_readlane_b32 s2, v108, 0
	v_readlane_b32 s3, v108, 32
	v_mov_b32_e32 v108, s4
	v_mov_b32_e32 v109, s9
	v_readlane_b32 s4, v110, 16
	v_readlane_b32 s9, v110, 48
	v_pk_add_f32 v[108:109], s[2:3], v[108:109]
	v_readlane_b32 s2, v110, 0
	v_readlane_b32 s3, v110, 32
	v_mov_b32_e32 v110, s4
	v_mov_b32_e32 v111, s9
	v_pk_add_f32 v[110:111], s[2:3], v[110:111]
	s_nop 0
	v_add_f32_e32 v140, v110, v111
	v_fmamk_f32 v123, v140, 0xba800000, v123
	v_fmac_f32_e32 v122, 0xba800000, v140
	v_fmamk_f32 v125, v140, 0xba800000, v125
	v_fmac_f32_e32 v124, 0xba800000, v140
	v_pk_mul_f32 v[110:111], v[124:125], v[124:125]
	v_pk_mul_f32 v[128:129], v[122:123], v[122:123]
	v_fmamk_f32 v117, v140, 0xba800000, v117
	v_pk_mov_b32 v[130:131], v[128:129], v[110:111] op_sel:[1,0]
	v_mov_b32_e32 v129, v111
	v_pk_add_f32 v[110:111], v[130:131], v[128:129]
	v_fmac_f32_e32 v116, 0xba800000, v140
	v_fmamk_f32 v119, v140, 0xba800000, v119
	v_fmac_f32_e32 v118, 0xba800000, v140
	v_pk_add_f32 v[110:111], v[110:111], v[110:111] op_sel_hi:[0,1]
	v_pk_mul_f32 v[128:129], v[118:119], v[118:119]
	v_pk_mul_f32 v[130:131], v[116:117], v[116:117]
	v_fmac_f32_e32 v136, 0xba800000, v140
	v_pk_mov_b32 v[138:139], v[130:131], v[128:129] op_sel:[1,0]
	v_mov_b32_e32 v131, v129
	v_fmamk_f32 v137, v140, 0xba800000, v137
	v_fmac_f32_e32 v112, 0xba800000, v140
	v_mul_f32_e32 v110, v136, v136
	v_pk_add_f32 v[128:129], v[138:139], v[130:131]
	v_fmamk_f32 v113, v140, 0xba800000, v113
	v_pk_fma_f32 v[130:131], v[136:137], v[136:137], v[110:111] op_sel_hi:[1,1,0]
	v_mul_f32_e32 v110, v112, v112
	v_pk_add_f32 v[128:129], v[128:129], v[128:129] op_sel_hi:[0,1]
	v_pk_fma_f32 v[138:139], v[112:113], v[112:113], v[110:111] op_sel_hi:[1,1,0]
	v_fmamk_f32 v105, v140, 0xba800000, v105
; #define GAS __attribute__((address_space(1)))
; #define LAS __attribute__((address_space(3)))
; __device__ __forceinline__ unsigned pk2(float lo, float hi) { typedef __bf16 bf2_t __attribute__((ext_vector_type(2))); const f32x2 v = {lo, hi}; return __builtin_bit_cast(unsigned, __builtin_convertvector(v, bf2_t)); }
; __device__ __forceinline__ unsigned dpp_swap1(unsigned v) { return (unsigned)__builtin_amdgcn_update_dpp(0, (int)v, 0xB1, 0xF, 0xF, true); }
; __device__ __forceinline__ void store_row_pk(bf16* rowp, int lane, const v2u (&o)[4]) {
;     const bool odd = (lane & 1) != 0; bf16* p = rowp + 4 * (lane & ~1) + (odd ? 256 : 0);
; #pragma unroll
;     for (int pr = 0; pr < 2; ++pr) { const v2u a = o[2 * pr], b = o[2 * pr + 1], send = odd ? a : b; v2u recv; recv.x = dpp_swap1(send.x); recv.y = dpp_swap1(send.y);
;         const v4u w = odd ? (v4u){recv.x, recv.y, b.x, b.y} : (v4u){a.x, a.y, recv.x, recv.y};
;         *(GAS v4u*)(p + 512 * pr) = w; }
; }
; __device__ __forceinline__ void p_r2(const Args& a, LAS unsigned char* lds, volatile LAS unsigned* MISC, int l, int wg, int G, int wave, int lane, int tid) {
;     ...
;             for (int r = 0; r < 2; ++r) ln_stats(x[r], mean[r], rstd[r]);
; #pragma unroll
;             for (int j = 0; j < 4; ++j) { const f32x4 g = *(const LAS f32x4*)(lds + R2_PAR + (1 * 256 + lane + 64 * j) * 16), bb = *(const LAS f32x4*)(lds + R2_PAR + (2 * 256 + lane + 64 * j) * 16);
; #pragma unroll
;                 for (int r = 0; r < 2; ++r) { x[r][j] = (x[r][j] - mean[r]) * rstd[r] * g + bb; ob[r][j].x = pk2(x[r][j][0], x[r][j][1]); ob[r][j].y = pk2(x[r][j][2], x[r][j][3]); } }
; #pragma unroll
;             for (int r = 0; r < 2; ++r) store_row_pk(X1 + (size_t)(t0 + r) * D, lane, ob[r]);
	v_fmac_f32_e32 v104, 0xba800000, v140
	v_fmamk_f32 v145, v140, 0xba800000, v145
	v_fmac_f32_e32 v144, 0xba800000, v140
	v_mul_f32_e32 v130, v144, v144
	v_mul_f32_e32 v138, v145, v145
	v_mul_f32_e32 v110, v104, v104
	v_mul_f32_e32 v128, v105, v105
	v_pk_add_f32 v[130:131], v[130:131], v[138:139]
	v_pk_add_f32 v[110:111], v[110:111], v[128:129]
	v_mov_b32_e32 v129, v108
	v_pk_add_f32 v[110:111], v[130:131], v[110:111]
	s_nop 0
	v_add_f32_e32 v110, v110, v111
	s_nop 1
	v_add_f32_dpp v110, v110, v110 quad_perm:[1,0,3,2] row_mask:0xf bank_mask:0xf bound_ctrl:1
	s_nop 1
	v_add_f32_dpp v110, v110, v110 quad_perm:[2,3,0,1] row_mask:0xf bank_mask:0xf bound_ctrl:1
	s_nop 1
	v_add_f32_dpp v110, v110, v110 row_half_mirror row_mask:0xf bank_mask:0xf bound_ctrl:1
	s_nop 1
	v_add_f32_dpp v110, v110, v110 row_mirror row_mask:0xf bank_mask:0xf bound_ctrl:1
	s_nop 0
	v_readlane_b32 s4, v110, 16
	v_readlane_b32 s9, v110, 48
	v_readlane_b32 s2, v110, 0
	v_readlane_b32 s3, v110, 32
	v_mov_b32_e32 v110, s4
	v_mov_b32_e32 v111, s9
	v_pk_add_f32 v[110:111], s[2:3], v[110:111]
	s_mov_b32 s2, 0x3727c5ac
	v_mov_b32_e32 v128, v110
	v_mov_b32_e32 v108, v111
	v_pk_add_f32 v[108:109], v[128:129], v[108:109]
	v_mov_b64_e32 v[142:143], s[2:3]
	v_pk_fma_f32 v[108:109], v[108:109], s[70:71], v[142:143] op_sel_hi:[1,0,0]
	s_ashr_i32 s9, s8, 31
	v_mul_f32_e32 v110, 0x4b800000, v109
	v_cmp_gt_f32_e64 s[54:55], s68, v109
	v_cmp_gt_f32_e32 vcc, s68, v108
	s_lshl_b64 s[2:3], s[8:9], 11
	v_cndmask_b32_e64 v109, v109, v110, s[54:55]
	v_rsq_f32_e32 v109, v109
	s_nop 0
	v_mul_f32_e32 v110, 0x45800000, v109
	v_cndmask_b32_e64 v188, v109, v110, s[54:55]
	v_mul_f32_e32 v109, 0x4b800000, v108
	v_cndmask_b32_e32 v108, v108, v109, vcc
	v_rsq_f32_e32 v108, v108
	v_pk_mul_f32 v[18:19], v[18:19], v[188:189] op_sel_hi:[1,0]
	v_pk_mul_f32 v[120:121], v[120:121], v[188:189] op_sel_hi:[1,0]
	v_mul_f32_e32 v109, 0x45800000, v108
	v_cndmask_b32_e32 v190, v108, v109, vcc
	ds_read_b128 v[108:111], v186 offset:4096
	ds_read_b128 v[148:151], v186 offset:8192
	s_waitcnt lgkmcnt(0)
	v_pk_fma_f32 v[138:139], v[120:121], v[110:111], v[150:151]
	v_pk_fma_f32 v[140:141], v[18:19], v[108:109], v[148:149]
	v_pk_mul_f32 v[18:19], v[122:123], v[190:191] op_sel_hi:[1,0]
	v_pk_mul_f32 v[120:121], v[124:125], v[190:191] op_sel_hi:[1,0]
	v_pk_fma_f32 v[130:131], v[108:109], v[18:19], v[148:149]
	v_pk_fma_f32 v[128:129], v[110:111], v[120:121], v[150:151]
	ds_read_b128 v[108:111], v186 offset:5120
	ds_read_b128 v[120:123], v186 offset:9216
	v_cvt_pk_bf16_f32 v189, v138, v139
	v_cvt_pk_bf16_f32 v191, v130, v131
	v_pk_mul_f32 v[18:19], v[126:127], v[188:189] op_sel_hi:[1,0]
	v_pk_mul_f32 v[124:125], v[132:133], v[188:189] op_sel_hi:[1,0]
	s_waitcnt lgkmcnt(0)
	v_pk_fma_f32 v[126:127], v[18:19], v[108:109], v[120:121]
	v_pk_mul_f32 v[18:19], v[116:117], v[190:191] op_sel_hi:[1,0]
	v_pk_mul_f32 v[116:117], v[118:119], v[190:191] op_sel_hi:[1,0]
	v_pk_fma_f32 v[124:125], v[124:125], v[110:111], v[122:123]
	v_pk_fma_f32 v[118:119], v[110:111], v[116:117], v[122:123]
	v_pk_fma_f32 v[120:121], v[108:109], v[18:19], v[120:121]
	ds_read_b128 v[108:111], v186 offset:6144
	ds_read_b128 v[148:151], v186 offset:10240
	v_pk_mul_f32 v[18:19], v[134:135], v[188:189] op_sel_hi:[1,0]
	v_pk_mul_f32 v[114:115], v[114:115], v[188:189] op_sel_hi:[1,0]
	v_pk_mul_f32 v[112:113], v[112:113], v[190:191] op_sel_hi:[1,0]
	v_cvt_pk_bf16_f32 v187, v140, v141
	s_waitcnt lgkmcnt(0)
	v_pk_fma_f32 v[116:117], v[18:19], v[108:109], v[148:149]
	v_pk_mul_f32 v[18:19], v[136:137], v[190:191] op_sel_hi:[1,0]
	v_pk_fma_f32 v[114:115], v[114:115], v[110:111], v[150:151]
	v_pk_fma_f32 v[110:111], v[110:111], v[112:113], v[150:151]
	v_pk_fma_f32 v[112:113], v[108:109], v[18:19], v[148:149]
	ds_read_b128 v[132:135], v186 offset:7168
	ds_read_b128 v[148:151], v186 offset:11264
	v_cvt_pk_bf16_f32 v193, v126, v127
	v_cvt_pk_bf16_f32 v194, v124, v125
	v_pk_mul_f32 v[18:19], v[146:147], v[188:189] op_sel_hi:[1,0]
	v_pk_mul_f32 v[122:123], v[144:145], v[190:191] op_sel_hi:[1,0]
	v_pk_mul_f32 v[106:107], v[106:107], v[188:189] op_sel_hi:[1,0]
	s_waitcnt lgkmcnt(0)
	v_pk_fma_f32 v[108:109], v[18:19], v[132:133], v[148:149]
	v_pk_mul_f32 v[18:19], v[104:105], v[190:191] op_sel_hi:[1,0]
	v_pk_fma_f32 v[104:105], v[132:133], v[122:123], v[148:149]
	v_cndmask_b32_e64 v132, v189, v194, s[44:45]
	v_cndmask_b32_e64 v133, v187, v193, s[44:45]
	v_pk_fma_f32 v[106:107], v[106:107], v[134:135], v[150:151]
	v_mov_b32_dpp v132, v132 quad_perm:[1,0,3,2] row_mask:0xf bank_mask:0xf bound_ctrl:1
	v_mov_b32_dpp v148, v133 quad_perm:[1,0,3,2] row_mask:0xf bank_mask:0xf bound_ctrl:1
	v_cvt_pk_bf16_f32 v197, v116, v117
	v_cvt_pk_bf16_f32 v202, v114, v115
	v_cvt_pk_bf16_f32 v146, v108, v109
	v_cvt_pk_bf16_f32 v147, v106, v107
	v_pk_fma_f32 v[18:19], v[134:135], v[18:19], v[150:151]
	v_lshl_add_u64 v[122:123], v[160:161], 0, s[2:3]
	v_cndmask_b32_e64 v135, v194, v132, s[44:45]
	v_cndmask_b32_e64 v134, v193, v148, s[44:45]
	v_cndmask_b32_e64 v133, v132, v189, s[44:45]
	v_cndmask_b32_e64 v132, v148, v187, s[44:45]
	global_store_dwordx4 v[122:123], v[132:135], off
	v_cvt_pk_bf16_f32 v192, v128, v129
	v_cvt_pk_bf16_f32 v195, v120, v121
	v_cndmask_b32_e64 v132, v202, v147, s[44:45]
	v_cndmask_b32_e64 v133, v197, v146, s[44:45]
	v_cvt_pk_bf16_f32 v196, v118, v119
	v_mov_b32_dpp v132, v132 quad_perm:[1,0,3,2] row_mask:0xf bank_mask:0xf bound_ctrl:1
	v_mov_b32_dpp v148, v133 quad_perm:[1,0,3,2] row_mask:0xf bank_mask:0xf bound_ctrl:1
	v_cndmask_b32_e64 v135, v147, v132, s[44:45]
	v_cndmask_b32_e64 v134, v146, v148, s[44:45]
	v_cndmask_b32_e64 v133, v132, v202, s[44:45]
	v_cndmask_b32_e64 v132, v148, v197, s[44:45]
; __device__ __forceinline__ void ln_stats(const f32x4 (&v)[4], float& mean, float& rstd) {
;     float s = 0.f;
; #pragma unroll
;     for (int j = 0; j < 4; ++j) s += (v[j][0] + v[j][1]) + (v[j][2] + v[j][3]);
;     mean = wave_sum(s) * (1.f / D); float q = 0.f;
; #pragma unroll
;     for (int j = 0; j < 4; ++j) { const f32x4 d = v[j] - mean; q += (d[0] * d[0] + d[1] * d[1]) + (d[2] * d[2] + d[3] * d[3]); }
;     rstd = rsqrtf(wave_sum(q) * (1.f / D) + LN_EPS);
; }
; __device__ __forceinline__ void p_r2(const Args& a, LAS unsigned char* lds, volatile LAS unsigned* MISC, int l, int wg, int G, int wave, int lane, int tid) {
;     ...
;             for (int r = 0; r < 2; ++r) store_row_pk(X1 + (size_t)(t0 + r) * D, lane, ob[r]);
; #pragma unroll
;             for (int r = 0; r < 2; ++r) ln_stats(x[r], mean[r], rstd[r]);
	s_add_i32 s2, s8, 1
	global_store_dwordx4 v[122:123], v[132:135], off offset:1024
	s_ashr_i32 s3, s2, 31
	s_lshl_b64 s[34:35], s[2:3], 11
	v_cndmask_b32_e64 v132, v192, v196, s[44:45]
	v_cndmask_b32_e64 v133, v191, v195, s[44:45]
	v_cvt_pk_bf16_f32 v136, v112, v113
	v_mov_b32_dpp v132, v132 quad_perm:[1,0,3,2] row_mask:0xf bank_mask:0xf bound_ctrl:1
	v_mov_b32_dpp v146, v133 quad_perm:[1,0,3,2] row_mask:0xf bank_mask:0xf bound_ctrl:1
	v_cvt_pk_bf16_f32 v137, v110, v111
	v_cvt_pk_bf16_f32 v144, v104, v105
	v_cvt_pk_bf16_f32 v145, v18, v19
	v_lshl_add_u64 v[122:123], v[160:161], 0, s[34:35]
	v_cndmask_b32_e64 v135, v196, v132, s[44:45]
	v_cndmask_b32_e64 v134, v195, v146, s[44:45]
	v_cndmask_b32_e64 v133, v132, v192, s[44:45]
	v_cndmask_b32_e64 v132, v146, v191, s[44:45]
	global_store_dwordx4 v[122:123], v[132:135], off
	s_lshl_b64 s[8:9], s[8:9], 10
	s_lshl_b64 s[2:3], s[2:3], 10
	v_cndmask_b32_e64 v132, v137, v145, s[44:45]
	v_cndmask_b32_e64 v133, v136, v144, s[44:45]
	s_nop 0
	v_mov_b32_dpp v132, v132 quad_perm:[1,0,3,2] row_mask:0xf bank_mask:0xf bound_ctrl:1
	v_mov_b32_dpp v146, v133 quad_perm:[1,0,3,2] row_mask:0xf bank_mask:0xf bound_ctrl:1
	v_cndmask_b32_e64 v135, v145, v132, s[44:45]
	v_cndmask_b32_e64 v134, v144, v146, s[44:45]
	v_cndmask_b32_e64 v133, v132, v137, s[44:45]
	v_cndmask_b32_e64 v132, v146, v136, s[44:45]
	global_store_dwordx4 v[122:123], v[132:135], off offset:1024
	v_pk_mov_b32 v[122:123], v[140:141], v[138:139] op_sel:[1,0]
	v_add_f32_e32 v136, v114, v115
	v_mov_b32_e32 v132, v140
	v_mov_b32_e32 v133, v139
	v_pk_add_f32 v[122:123], v[122:123], v[132:133]
	v_pk_mov_b32 v[132:133], v[126:127], v[124:125] op_sel:[1,0]
	v_mov_b32_e32 v134, v126
	v_mov_b32_e32 v135, v125
	v_pk_add_f32 v[132:133], v[132:133], v[134:135]
	v_add_f32_e32 v122, v122, v123
	v_pk_add_f32 v[132:133], v[132:133], v[132:133] op_sel:[0,1] op_sel_hi:[1,0]
	v_add_f32_e32 v122, 0, v122
	v_add_f32_e32 v134, v116, v117
	v_mov_b32_e32 v123, v108
	v_mov_b32_e32 v133, v109
	v_mov_b32_e32 v135, v106
	v_mov_b32_e32 v137, v107
	v_pk_add_f32 v[122:123], v[122:123], v[132:133]
	v_pk_add_f32 v[132:133], v[134:135], v[136:137]
	v_add_f32_e32 v145, v110, v111
	v_pk_add_f32 v[122:123], v[122:123], v[132:133]
	s_nop 0
	v_add_f32_e32 v122, v122, v123
	s_nop 1
	v_add_f32_dpp v122, v122, v122 quad_perm:[1,0,3,2] row_mask:0xf bank_mask:0xf bound_ctrl:1
	s_nop 1
	v_add_f32_dpp v122, v122, v122 quad_perm:[2,3,0,1] row_mask:0xf bank_mask:0xf bound_ctrl:1
	s_nop 1
	v_add_f32_dpp v122, v122, v122 row_half_mirror row_mask:0xf bank_mask:0xf bound_ctrl:1
	s_nop 1
	v_add_f32_dpp v122, v122, v122 row_mirror row_mask:0xf bank_mask:0xf bound_ctrl:1
	s_nop 0
	v_readlane_b32 s4, v122, 16
	v_readlane_b32 s25, v122, 48
	v_readlane_b32 s34, v122, 0
	v_readlane_b32 s35, v122, 32
	v_mov_b32_e32 v122, s4
	v_mov_b32_e32 v123, s25
	v_pk_add_f32 v[122:123], s[34:35], v[122:123]
	s_nop 0
	v_add_f32_e32 v144, v122, v123
	v_fmamk_f32 v141, v144, 0xba800000, v141
	v_fmac_f32_e32 v140, 0xba800000, v144
	v_fmamk_f32 v139, v144, 0xba800000, v139
	v_fmac_f32_e32 v138, 0xba800000, v144
	v_pk_mul_f32 v[122:123], v[138:139], v[138:139]
	v_pk_mul_f32 v[132:133], v[140:141], v[140:141]
	v_fmamk_f32 v127, v144, 0xba800000, v127
	v_pk_mov_b32 v[134:135], v[132:133], v[122:123] op_sel:[1,0]
	v_mov_b32_e32 v133, v123
	v_pk_add_f32 v[122:123], v[134:135], v[132:133]
	v_fmac_f32_e32 v126, 0xba800000, v144
	v_fmamk_f32 v125, v144, 0xba800000, v125
	v_fmac_f32_e32 v124, 0xba800000, v144
	v_pk_add_f32 v[122:123], v[122:123], v[122:123] op_sel_hi:[0,1]
	v_pk_mul_f32 v[132:133], v[124:125], v[124:125]
	v_pk_mul_f32 v[134:135], v[126:127], v[126:127]
	v_fmac_f32_e32 v116, 0xba800000, v144
	v_pk_mov_b32 v[136:137], v[134:135], v[132:133] op_sel:[1,0]
	v_mov_b32_e32 v135, v133
	v_fmamk_f32 v117, v144, 0xba800000, v117
	v_fmac_f32_e32 v114, 0xba800000, v144
	v_mul_f32_e32 v122, v116, v116
	v_pk_add_f32 v[132:133], v[136:137], v[134:135]
	v_fmamk_f32 v115, v144, 0xba800000, v115
	v_pk_fma_f32 v[134:135], v[116:117], v[116:117], v[122:123] op_sel_hi:[1,1,0]
	v_mul_f32_e32 v122, v114, v114
	v_pk_add_f32 v[132:133], v[132:133], v[132:133] op_sel_hi:[0,1]
	v_pk_fma_f32 v[136:137], v[114:115], v[114:115], v[122:123] op_sel_hi:[1,1,0]
	v_fmamk_f32 v107, v144, 0xba800000, v107
	v_fmac_f32_e32 v106, 0xba800000, v144
	v_fmamk_f32 v109, v144, 0xba800000, v109
	v_fmac_f32_e32 v108, 0xba800000, v144
	v_mul_f32_e32 v134, v108, v108
	v_mul_f32_e32 v136, v109, v109
	v_mul_f32_e32 v122, v106, v106
	v_mul_f32_e32 v132, v107, v107
	v_pk_add_f32 v[134:135], v[134:135], v[136:137]
	v_pk_add_f32 v[122:123], v[122:123], v[132:133]
	v_pk_mov_b32 v[132:133], v[130:131], v[128:129] op_sel:[1,0]
	v_pk_add_f32 v[122:123], v[134:135], v[122:123]
	v_mov_b32_e32 v134, v130
	v_mov_b32_e32 v135, v129
	v_pk_add_f32 v[132:133], v[132:133], v[134:135]
	v_pk_mov_b32 v[134:135], v[120:121], v[118:119] op_sel:[1,0]
	v_mov_b32_e32 v136, v120
	v_mov_b32_e32 v137, v119
	v_pk_add_f32 v[134:135], v[134:135], v[136:137]
	v_add_f32_e32 v132, v132, v133
	v_pk_add_f32 v[134:135], v[134:135], v[134:135] op_sel_hi:[0,1]
	v_add_f32_e32 v133, 0, v132
	v_add_f32_e32 v137, v112, v113
	v_mov_b32_e32 v136, v104
	v_mov_b32_e32 v144, v105
	v_mov_b32_e32 v134, v18
	v_mov_b32_e32 v132, v19
	v_pk_add_f32 v[136:137], v[136:137], v[144:145]
	v_pk_add_f32 v[132:133], v[134:135], v[132:133]
	v_add_f32_e32 v122, v122, v123
	v_pk_add_f32 v[132:133], v[136:137], v[132:133]
	s_nop 0
	v_add_f32_dpp v122, v122, v122 quad_perm:[1,0,3,2] row_mask:0xf bank_mask:0xf bound_ctrl:1
	v_add_f32_e32 v132, v132, v133
	s_nop 0
	v_add_f32_dpp v122, v122, v122 quad_perm:[2,3,0,1] row_mask:0xf bank_mask:0xf bound_ctrl:1
; #define LAS __attribute__((address_space(3)))
; __device__ __forceinline__ void ln_stats(const f32x4 (&v)[4], float& mean, float& rstd) {
;     float s = 0.f;
; #pragma unroll
;     for (int j = 0; j < 4; ++j) s += (v[j][0] + v[j][1]) + (v[j][2] + v[j][3]);
;     mean = wave_sum(s) * (1.f / D); float q = 0.f;
; #pragma unroll
;     for (int j = 0; j < 4; ++j) { const f32x4 d = v[j] - mean; q += (d[0] * d[0] + d[1] * d[1]) + (d[2] * d[2] + d[3] * d[3]); }
;     rstd = rsqrtf(wave_sum(q) * (1.f / D) + LN_EPS);
; }
; __device__ __forceinline__ void p_r2(const Args& a, LAS unsigned char* lds, volatile LAS unsigned* MISC, int l, int wg, int G, int wave, int lane, int tid) {
;     ...
;             for (int r = 0; r < 2; ++r) ln_stats(x[r], mean[r], rstd[r]);
; #pragma unroll
;             for (int j = 0; j < 4; ++j) { const f32x4 s1 = *(const LAS f32x4*)(lds + R2_PAR + (3 * 256 + lane + 64 * j) * 16), s0 = *(const LAS f32x4*)(lds + R2_PAR + (4 * 256 + lane + 64 * j) * 16);
	v_add_f32_dpp v132, v132, v132 quad_perm:[1,0,3,2] row_mask:0xf bank_mask:0xf bound_ctrl:1
	s_nop 0
	v_add_f32_dpp v122, v122, v122 row_half_mirror row_mask:0xf bank_mask:0xf bound_ctrl:1
	v_add_f32_dpp v132, v132, v132 quad_perm:[2,3,0,1] row_mask:0xf bank_mask:0xf bound_ctrl:1
	s_nop 0
	v_add_f32_dpp v122, v122, v122 row_mirror row_mask:0xf bank_mask:0xf bound_ctrl:1
	v_add_f32_dpp v132, v132, v132 row_half_mirror row_mask:0xf bank_mask:0xf bound_ctrl:1
	v_readlane_b32 s4, v122, 16
	v_readlane_b32 s25, v122, 48
	v_add_f32_dpp v132, v132, v132 row_mirror row_mask:0xf bank_mask:0xf bound_ctrl:1
	v_readlane_b32 s34, v122, 0
	v_readlane_b32 s35, v122, 32
	v_mov_b32_e32 v122, s4
	v_mov_b32_e32 v123, s25
	v_readlane_b32 s4, v132, 16
	v_readlane_b32 s25, v132, 48
	v_pk_add_f32 v[122:123], s[34:35], v[122:123]
	v_readlane_b32 s34, v132, 0
	v_readlane_b32 s35, v132, 32
	v_mov_b32_e32 v132, s4
	v_mov_b32_e32 v133, s25
	v_pk_add_f32 v[132:133], s[34:35], v[132:133]
	s_nop 0
	v_add_f32_e32 v146, v132, v133
	v_fmamk_f32 v131, v146, 0xba800000, v131
	v_fmac_f32_e32 v130, 0xba800000, v146
	v_fmamk_f32 v129, v146, 0xba800000, v129
	v_fmac_f32_e32 v128, 0xba800000, v146
	v_pk_mul_f32 v[132:133], v[128:129], v[128:129]
	v_pk_mul_f32 v[134:135], v[130:131], v[130:131]
	v_fmamk_f32 v121, v146, 0xba800000, v121
	v_pk_mov_b32 v[136:137], v[134:135], v[132:133] op_sel:[1,0]
	v_mov_b32_e32 v135, v133
	v_pk_add_f32 v[132:133], v[136:137], v[134:135]
	v_fmac_f32_e32 v120, 0xba800000, v146
	v_fmamk_f32 v119, v146, 0xba800000, v119
	v_fmac_f32_e32 v118, 0xba800000, v146
	v_pk_add_f32 v[132:133], v[132:133], v[132:133] op_sel_hi:[0,1]
	v_pk_mul_f32 v[134:135], v[118:119], v[118:119]
	v_pk_mul_f32 v[136:137], v[120:121], v[120:121]
	v_fmac_f32_e32 v112, 0xba800000, v146
	v_pk_mov_b32 v[144:145], v[136:137], v[134:135] op_sel:[1,0]
	v_mov_b32_e32 v137, v135
	v_fmamk_f32 v113, v146, 0xba800000, v113
	v_fmac_f32_e32 v110, 0xba800000, v146
	v_mul_f32_e32 v132, v112, v112
	v_pk_add_f32 v[134:135], v[144:145], v[136:137]
	v_fmamk_f32 v111, v146, 0xba800000, v111
	v_pk_fma_f32 v[136:137], v[112:113], v[112:113], v[132:133] op_sel_hi:[1,1,0]
	v_mul_f32_e32 v132, v110, v110
	v_pk_add_f32 v[134:135], v[134:135], v[134:135] op_sel_hi:[0,1]
	v_pk_fma_f32 v[144:145], v[110:111], v[110:111], v[132:133] op_sel_hi:[1,1,0]
	v_fmamk_f32 v19, v146, 0xba800000, v19
	v_fmac_f32_e32 v18, 0xba800000, v146
	v_fmamk_f32 v105, v146, 0xba800000, v105
	v_fmac_f32_e32 v104, 0xba800000, v146
	v_mul_f32_e32 v136, v104, v104
	v_mul_f32_e32 v144, v105, v105
	v_mul_f32_e32 v132, v18, v18
	v_mul_f32_e32 v134, v19, v19
	v_pk_add_f32 v[136:137], v[136:137], v[144:145]
	v_pk_add_f32 v[132:133], v[132:133], v[134:135]
	v_mov_b32_e32 v135, v122
	v_pk_add_f32 v[132:133], v[136:137], v[132:133]
	s_nop 0
	v_add_f32_e32 v132, v132, v133
	s_nop 1
	v_add_f32_dpp v132, v132, v132 quad_perm:[1,0,3,2] row_mask:0xf bank_mask:0xf bound_ctrl:1
	s_nop 1
	v_add_f32_dpp v132, v132, v132 quad_perm:[2,3,0,1] row_mask:0xf bank_mask:0xf bound_ctrl:1
	s_nop 1
	v_add_f32_dpp v132, v132, v132 row_half_mirror row_mask:0xf bank_mask:0xf bound_ctrl:1
	s_nop 1
	v_add_f32_dpp v132, v132, v132 row_mirror row_mask:0xf bank_mask:0xf bound_ctrl:1
	s_nop 0
	v_readlane_b32 s4, v132, 16
	v_readlane_b32 s25, v132, 48
	v_readlane_b32 s34, v132, 0
	v_readlane_b32 s35, v132, 32
	v_mov_b32_e32 v132, s4
	v_mov_b32_e32 v133, s25
	v_pk_add_f32 v[132:133], s[34:35], v[132:133]
	s_nop 0
	v_mov_b32_e32 v134, v132
	v_mov_b32_e32 v122, v133
	v_pk_add_f32 v[122:123], v[134:135], v[122:123]
	s_nop 0
	v_pk_fma_f32 v[122:123], v[122:123], s[70:71], v[142:143] op_sel_hi:[1,0,0]
	ds_read_b128 v[134:137], v186 offset:12288
	ds_read_b128 v[142:145], v186 offset:16384
	v_mul_f32_e32 v132, 0x4b800000, v123
	v_cmp_gt_f32_e64 s[54:55], s68, v123
	v_cmp_gt_f32_e32 vcc, s68, v122
	s_waitcnt lgkmcnt(1)
	v_pk_add_f32 v[134:135], v[134:135], 1.0 op_sel_hi:[1,0]
	v_cndmask_b32_e64 v123, v123, v132, s[54:55]
	v_rsq_f32_e32 v123, v123
	v_pk_add_f32 v[136:137], v[136:137], 1.0 op_sel_hi:[1,0]
	v_mul_f32_e32 v132, 0x45800000, v123
	v_cndmask_b32_e64 v132, v123, v132, s[54:55]
	v_mul_f32_e32 v123, 0x4b800000, v122
	v_cndmask_b32_e32 v122, v122, v123, vcc
	v_rsq_f32_e32 v122, v122
	v_pk_mul_f32 v[140:141], v[140:141], v[132:133] op_sel_hi:[1,0]
	v_pk_mul_f32 v[138:139], v[138:139], v[132:133] op_sel_hi:[1,0]
	s_waitcnt lgkmcnt(0)
; __device__ __forceinline__ unsigned pk4_fp8(float a, float b, float c, float d) { int w = 0; w = __builtin_amdgcn_cvt_pk_fp8_f32(a, b, w, false); w = __builtin_amdgcn_cvt_pk_fp8_f32(c, d, w, true); return (unsigned)w; }
; #define LAS __attribute__((address_space(3)))
; __device__ __forceinline__ unsigned pk4_fp8(float a, float b, float c, float d) { int w = 0; w = __builtin_amdgcn_cvt_pk_fp8_f32(a, b, w, false); w = __builtin_amdgcn_cvt_pk_fp8_f32(c, d, w, true); return (unsigned)w; }
; __device__ __forceinline__ void p_r2(const Args& a, LAS unsigned char* lds, volatile LAS unsigned* MISC, int l, int wg, int G, int wave, int lane, int tid) {
;     ...
;             for (int j = 0; j < 4; ++j) { const f32x4 s1 = *(const LAS f32x4*)(lds + R2_PAR + (3 * 256 + lane + 64 * j) * 16), s0 = *(const LAS f32x4*)(lds + R2_PAR + (4 * 256 + lane + 64 * j) * 16);
; #pragma unroll
;                 for (int r = 0; r < 2; ++r) { u[r][j] = (x[r][j] - mean[r]) * rstd[r] * (1.0f + s1) + s0;
;                     uq[r][j] = pk4_fp8(u[r][j][0] * F8_SA1, u[r][j][1] * F8_SA1, u[r][j][2] * F8_SA1, u[r][j][3] * F8_SA1);
;                     const h16x2 h0 = __builtin_amdgcn_cvt_pkrtz(u[r][j][0], u[r][j][1]), h1 = __builtin_amdgcn_cvt_pkrtz(u[r][j][2], u[r][j][3]);
;                     const h16x2 l0 = __builtin_amdgcn_cvt_pkrtz(u[r][j][0] - (float)h0[0], u[r][j][1] - (float)h0[1]), l1 = __builtin_amdgcn_cvt_pkrtz(u[r][j][2] - (float)h1[0], u[r][j][3] - (float)h1[1]);
;                     const int row = 2 * wave + r, off = row * 2048 + ((((lane >> 1) + 32 * j) ^ (row & 15)) << 4) + 8 * (lane & 1);
;                     *(LAS v2u*)(lds + R2_UH + off) = (v2u){__builtin_bit_cast(unsigned, h0), __builtin_bit_cast(unsigned, h1)};
;                     *(LAS v2u*)(lds + R2_UL + off) = (v2u){__builtin_bit_cast(unsigned, l0), __builtin_bit_cast(unsigned, l1)}; } }
	v_pk_fma_f32 v[140:141], v[140:141], v[134:135], v[142:143]
	v_mul_f32_e32 v123, 0x45800000, v122
	v_cndmask_b32_e32 v122, v122, v123, vcc
	v_mul_f32_e32 v133, 4.0, v140
	v_mul_f32_e32 v146, 4.0, v141
	v_cvt_pk_fp8_f32 v123, v133, v146
	v_cvt_pkrtz_f16_f32 v146, v140, v141
	v_cvt_f32_f16_e32 v133, v146
	v_pk_fma_f32 v[138:139], v[138:139], v[136:137], v[144:145]
	v_sub_f32_e32 v133, v140, v133
	v_cvt_f32_f16_sdwa v140, v146 dst_sel:DWORD dst_unused:UNUSED_PAD src0_sel:WORD_1
	v_mul_f32_e32 v147, 4.0, v138
	v_mul_f32_e32 v148, 4.0, v139
	v_cvt_pk_fp8_f32 v123, v147, v148 op_sel:[0,0,1]
	v_cvt_pkrtz_f16_f32 v147, v138, v139
	v_sub_f32_e32 v140, v141, v140
	v_cvt_pkrtz_f16_f32 v140, v133, v140
	v_cvt_f32_f16_e32 v133, v147
	v_pk_mul_f32 v[130:131], v[130:131], v[122:123] op_sel_hi:[1,0]
	v_pk_mul_f32 v[128:129], v[128:129], v[122:123] op_sel_hi:[1,0]
	v_pk_fma_f32 v[130:131], v[134:135], v[130:131], v[142:143]
	v_sub_f32_e32 v133, v138, v133
	v_cvt_f32_f16_sdwa v138, v147 dst_sel:DWORD dst_unused:UNUSED_PAD src0_sel:WORD_1
	v_pk_fma_f32 v[136:137], v[136:137], v[128:129], v[144:145]
	v_mul_f32_e32 v129, 4.0, v130
	v_sub_f32_e32 v138, v139, v138
	v_cvt_pkrtz_f16_f32 v141, v133, v138
	v_mul_f32_e32 v133, 4.0, v131
	v_cvt_pk_fp8_f32 v128, v129, v133
	v_mul_f32_e32 v134, 4.0, v136
	v_mul_f32_e32 v135, 4.0, v137
	ds_write2st64_b64 v172, v[146:147], v[140:141] offset1:64
	v_cvt_pk_fp8_f32 v128, v134, v135 op_sel:[0,0,1]
	v_cvt_pkrtz_f16_f32 v134, v130, v131
	v_cvt_f32_f16_e32 v129, v134
	v_cvt_pkrtz_f16_f32 v135, v136, v137
	v_pk_mul_f32 v[126:127], v[126:127], v[132:133] op_sel_hi:[1,0]
	v_pk_mul_f32 v[124:125], v[124:125], v[132:133] op_sel_hi:[1,0]
	v_sub_f32_e32 v129, v130, v129
	v_cvt_f32_f16_sdwa v130, v134 dst_sel:DWORD dst_unused:UNUSED_PAD src0_sel:WORD_1
	v_pk_mul_f32 v[120:121], v[120:121], v[122:123] op_sel_hi:[1,0]
	v_pk_mul_f32 v[118:119], v[118:119], v[122:123] op_sel_hi:[1,0]
	v_pk_mul_f32 v[112:113], v[112:113], v[122:123] op_sel_hi:[1,0]
	v_sub_f32_e32 v130, v131, v130
	v_cvt_pkrtz_f16_f32 v130, v129, v130
	v_cvt_f32_f16_e32 v129, v135
	v_cvt_f32_f16_sdwa v131, v135 dst_sel:DWORD dst_unused:UNUSED_PAD src0_sel:WORD_1
	v_pk_mul_f32 v[110:111], v[110:111], v[122:123] op_sel_hi:[1,0]
	v_pk_mul_f32 v[104:105], v[104:105], v[122:123] op_sel_hi:[1,0]
	v_sub_f32_e32 v129, v136, v129
	v_sub_f32_e32 v131, v137, v131
	v_cvt_pkrtz_f16_f32 v131, v129, v131
	ds_write2st64_b64 v173, v[134:135], v[130:131] offset1:64
	ds_read_b128 v[134:137], v186 offset:13312
	ds_read_b128 v[138:141], v186 offset:17408
	v_pk_mul_f32 v[18:19], v[18:19], v[122:123] op_sel_hi:[1,0]
	s_waitcnt lgkmcnt(1)
	v_pk_add_f32 v[134:135], v[134:135], 1.0 op_sel_hi:[1,0]
	v_pk_add_f32 v[130:131], v[136:137], 1.0 op_sel_hi:[1,0]
	s_waitcnt lgkmcnt(0)
	v_pk_fma_f32 v[126:127], v[126:127], v[134:135], v[138:139]
	v_pk_fma_f32 v[136:137], v[124:125], v[130:131], v[140:141]
	v_mul_f32_e32 v125, 4.0, v126
	v_mul_f32_e32 v129, 4.0, v127
	v_cvt_pk_fp8_f32 v124, v125, v129
	v_mul_f32_e32 v133, 4.0, v136
	v_mul_f32_e32 v142, 4.0, v137
	v_cvt_pkrtz_f16_f32 v143, v136, v137
	v_cvt_pk_fp8_f32 v124, v133, v142 op_sel:[0,0,1]
	v_cvt_pkrtz_f16_f32 v142, v126, v127
	v_cvt_f32_f16_e32 v125, v142
	v_pk_fma_f32 v[120:121], v[134:135], v[120:121], v[138:139]
	v_pk_fma_f32 v[118:119], v[130:131], v[118:119], v[140:141]
	v_sub_f32_e32 v125, v126, v125
	v_cvt_f32_f16_sdwa v126, v142 dst_sel:DWORD dst_unused:UNUSED_PAD src0_sel:WORD_1
	v_mul_f32_e32 v129, 4.0, v119
	v_pk_mul_f32 v[116:117], v[116:117], v[132:133] op_sel_hi:[1,0]
	v_sub_f32_e32 v126, v127, v126
	v_cvt_pkrtz_f16_f32 v126, v125, v126
	v_cvt_f32_f16_e32 v125, v143
	v_cvt_f32_f16_sdwa v127, v143 dst_sel:DWORD dst_unused:UNUSED_PAD src0_sel:WORD_1
	v_pk_mul_f32 v[114:115], v[114:115], v[132:133] op_sel_hi:[1,0]
	v_pk_mul_f32 v[108:109], v[108:109], v[132:133] op_sel_hi:[1,0]
	v_sub_f32_e32 v125, v136, v125
	v_sub_f32_e32 v127, v137, v127
	v_cvt_pkrtz_f16_f32 v127, v125, v127
	ds_write2st64_b64 v174, v[142:143], v[126:127] offset1:64
	v_mul_f32_e32 v125, 4.0, v120
	v_mul_f32_e32 v126, 4.0, v121
	v_cvt_pk_fp8_f32 v130, v125, v126
	v_cvt_pkrtz_f16_f32 v126, v120, v121
	v_cvt_f32_f16_e32 v125, v126
	v_mul_f32_e32 v127, 4.0, v118
	v_cvt_pk_fp8_f32 v130, v127, v129 op_sel:[0,0,1]
	v_cvt_pkrtz_f16_f32 v127, v118, v119
	v_sub_f32_e32 v120, v120, v125
	v_cvt_f32_f16_sdwa v125, v126 dst_sel:DWORD dst_unused:UNUSED_PAD src0_sel:WORD_1
	v_pk_mul_f32 v[106:107], v[106:107], v[132:133] op_sel_hi:[1,0]
	v_sub_f32_e32 v121, v121, v125
	v_cvt_pkrtz_f16_f32 v120, v120, v121
	v_cvt_f32_f16_e32 v121, v127
	v_sub_f32_e32 v118, v118, v121
	v_cvt_f32_f16_sdwa v121, v127 dst_sel:DWORD dst_unused:UNUSED_PAD src0_sel:WORD_1
	v_sub_f32_e32 v119, v119, v121
	v_cvt_pkrtz_f16_f32 v121, v118, v119
	ds_write2st64_b64 v175, v[126:127], v[120:121] offset1:64
	ds_read_b128 v[118:121], v186 offset:14336
	ds_read_b128 v[134:137], v186 offset:18432
	s_waitcnt lgkmcnt(1)
	v_pk_add_f32 v[118:119], v[118:119], 1.0 op_sel_hi:[1,0]
	s_waitcnt lgkmcnt(0)
; #define GAS __attribute__((address_space(1)))
; #define LAS __attribute__((address_space(3)))
; __device__ __forceinline__ void store_row_q8(unsigned char* rowp, int lane, const unsigned (&d)[4]) {
;     const bool o1 = (lane & 1) != 0, o2 = (lane & 2) != 0;
;     unsigned p[2][2];
; #pragma unroll
;     for (int cc = 0; cc < 2; ++cc) { const unsigned keep = o1 ? d[2 * cc + 1] : d[2 * cc], send = o1 ? d[2 * cc] : d[2 * cc + 1], recv = dpp_swap1(send); p[cc][0] = o1 ? recv : keep; p[cc][1] = o1 ? keep : recv; }
;     const unsigned s0 = o2 ? p[0][0] : p[1][0], s1 = o2 ? p[0][1] : p[1][1], r0 = dpp_swap2(s0), r1 = dpp_swap2(s1);
;     const v4u w = o2 ? (v4u){r0, r1, p[1][0], p[1][1]} : (v4u){p[0][0], p[0][1], r0, r1};
;     *(GAS v4u*)(rowp + 16 * (lane >> 2) + 256 * (lane & 3)) = w;
; }
; __device__ __forceinline__ void p_r2(const Args& a, LAS unsigned char* lds, volatile LAS unsigned* MISC, int l, int wg, int G, int wave, int lane, int tid) {
;     ...
;             for (int j = 0; j < 4; ++j) { const f32x4 s1 = *(const LAS f32x4*)(lds + R2_PAR + (3 * 256 + lane + 64 * j) * 16), s0 = *(const LAS f32x4*)(lds + R2_PAR + (4 * 256 + lane + 64 * j) * 16);
; #pragma unroll
;                 for (int r = 0; r < 2; ++r) { u[r][j] = (x[r][j] - mean[r]) * rstd[r] * (1.0f + s1) + s0;
;                     uq[r][j] = pk4_fp8(u[r][j][0] * F8_SA1, u[r][j][1] * F8_SA1, u[r][j][2] * F8_SA1, u[r][j][3] * F8_SA1);
;                     const h16x2 h0 = __builtin_amdgcn_cvt_pkrtz(u[r][j][0], u[r][j][1]), h1 = __builtin_amdgcn_cvt_pkrtz(u[r][j][2], u[r][j][3]);
;                     const h16x2 l0 = __builtin_amdgcn_cvt_pkrtz(u[r][j][0] - (float)h0[0], u[r][j][1] - (float)h0[1]), l1 = __builtin_amdgcn_cvt_pkrtz(u[r][j][2] - (float)h1[0], u[r][j][3] - (float)h1[1]);
;                     const int row = 2 * wave + r, off = row * 2048 + ((((lane >> 1) + 32 * j) ^ (row & 15)) << 4) + 8 * (lane & 1);
;                     *(LAS v2u*)(lds + R2_UH + off) = (v2u){__builtin_bit_cast(unsigned, h0), __builtin_bit_cast(unsigned, h1)};
;                     *(LAS v2u*)(lds + R2_UL + off) = (v2u){__builtin_bit_cast(unsigned, l0), __builtin_bit_cast(unsigned, l1)}; } }
; #pragma unroll
;             for (int r = 0; r < 2; ++r) store_row_q8(U8 + (size_t)(t0 + r) * D, lane, uq[r]);
	v_pk_fma_f32 v[116:117], v[116:117], v[118:119], v[134:135]
	v_pk_add_f32 v[120:121], v[120:121], 1.0 op_sel_hi:[1,0]
	v_mul_f32_e32 v125, 4.0, v116
	v_mul_f32_e32 v126, 4.0, v117
	v_cvt_pk_fp8_f32 v131, v125, v126
	v_cvt_pkrtz_f16_f32 v126, v116, v117
	v_cvt_f32_f16_e32 v125, v126
	v_pk_fma_f32 v[114:115], v[114:115], v[120:121], v[136:137]
	v_pk_fma_f32 v[112:113], v[112:113], v[118:119], v[134:135]
	v_mul_f32_e32 v127, 4.0, v114
	v_sub_f32_e32 v116, v116, v125
	v_cvt_f32_f16_sdwa v125, v126 dst_sel:DWORD dst_unused:UNUSED_PAD src0_sel:WORD_1
	v_mul_f32_e32 v129, 4.0, v115
	v_cvt_pk_fp8_f32 v131, v127, v129 op_sel:[0,0,1]
	v_cvt_pkrtz_f16_f32 v127, v114, v115
	v_sub_f32_e32 v117, v117, v125
	v_cvt_pkrtz_f16_f32 v116, v116, v117
	v_cvt_f32_f16_e32 v117, v127
	v_pk_fma_f32 v[110:111], v[110:111], v[120:121], v[136:137]
	v_sub_f32_e32 v114, v114, v117
	v_cvt_f32_f16_sdwa v117, v127 dst_sel:DWORD dst_unused:UNUSED_PAD src0_sel:WORD_1
	v_sub_f32_e32 v115, v115, v117
	v_cvt_pkrtz_f16_f32 v117, v114, v115
	v_mul_f32_e32 v114, 4.0, v112
	v_mul_f32_e32 v115, 4.0, v113
	v_cvt_pk_fp8_f32 v120, v114, v115
	ds_write2st64_b64 v176, v[126:127], v[116:117] offset1:64
	v_mul_f32_e32 v116, 4.0, v110
	v_mul_f32_e32 v117, 4.0, v111
	v_cvt_pkrtz_f16_f32 v114, v112, v113
	v_cvt_pk_fp8_f32 v120, v116, v117 op_sel:[0,0,1]
	v_cvt_f32_f16_e32 v116, v114
	v_cvt_pkrtz_f16_f32 v115, v110, v111
	v_sub_f32_e32 v112, v112, v116
	v_cvt_f32_f16_sdwa v116, v114 dst_sel:DWORD dst_unused:UNUSED_PAD src0_sel:WORD_1
	v_sub_f32_e32 v113, v113, v116
	v_cvt_pkrtz_f16_f32 v112, v112, v113
	v_cvt_f32_f16_e32 v113, v115
	v_sub_f32_e32 v110, v110, v113
	v_cvt_f32_f16_sdwa v113, v115 dst_sel:DWORD dst_unused:UNUSED_PAD src0_sel:WORD_1
	v_sub_f32_e32 v111, v111, v113
	v_cvt_pkrtz_f16_f32 v113, v110, v111
	ds_write2st64_b64 v177, v[114:115], v[112:113] offset1:64
	ds_read_b128 v[110:113], v186 offset:15360
	ds_read_b128 v[114:117], v186 offset:19456
	s_waitcnt lgkmcnt(1)
	v_pk_add_f32 v[110:111], v[110:111], 1.0 op_sel_hi:[1,0]
	s_waitcnt lgkmcnt(0)
	v_pk_fma_f32 v[108:109], v[108:109], v[110:111], v[114:115]
	v_pk_add_f32 v[112:113], v[112:113], 1.0 op_sel_hi:[1,0]
	v_mul_f32_e32 v118, 4.0, v108
	v_mul_f32_e32 v119, 4.0, v109
	v_cvt_pk_fp8_f32 v126, v118, v119
	v_pk_fma_f32 v[106:107], v[106:107], v[112:113], v[116:117]
	v_cvt_pkrtz_f16_f32 v118, v108, v109
	v_mul_f32_e32 v121, 4.0, v106
	v_mul_f32_e32 v125, 4.0, v107
	v_cvt_pk_fp8_f32 v126, v121, v125 op_sel:[0,0,1]
	v_cvt_f32_f16_e32 v121, v118
	v_cvt_pkrtz_f16_f32 v119, v106, v107
	v_pk_fma_f32 v[104:105], v[104:105], v[110:111], v[114:115]
	v_sub_f32_e32 v108, v108, v121
	v_cvt_f32_f16_sdwa v121, v118 dst_sel:DWORD dst_unused:UNUSED_PAD src0_sel:WORD_1
	v_pk_fma_f32 v[18:19], v[18:19], v[112:113], v[116:117]
	v_sub_f32_e32 v109, v109, v121
	v_cvt_pkrtz_f16_f32 v108, v108, v109
	v_cvt_f32_f16_e32 v109, v119
	v_sub_f32_e32 v106, v106, v109
	v_cvt_f32_f16_sdwa v109, v119 dst_sel:DWORD dst_unused:UNUSED_PAD src0_sel:WORD_1
	v_sub_f32_e32 v107, v107, v109
	v_cvt_pkrtz_f16_f32 v109, v106, v107
	v_mul_f32_e32 v106, 4.0, v104
	v_mul_f32_e32 v107, 4.0, v105
	v_cvt_pk_fp8_f32 v110, v106, v107
	ds_write2st64_b64 v178, v[118:119], v[108:109] offset1:64
	v_mul_f32_e32 v108, 4.0, v18
	v_mul_f32_e32 v109, 4.0, v19
	v_cvt_pkrtz_f16_f32 v106, v104, v105
	v_cvt_pk_fp8_f32 v110, v108, v109 op_sel:[0,0,1]
	v_cvt_f32_f16_e32 v108, v106
	v_cvt_pkrtz_f16_f32 v107, v18, v19
	v_sub_f32_e32 v104, v104, v108
	v_cvt_f32_f16_sdwa v108, v106 dst_sel:DWORD dst_unused:UNUSED_PAD src0_sel:WORD_1
	v_sub_f32_e32 v105, v105, v108
	v_cvt_pkrtz_f16_f32 v104, v104, v105
	v_cvt_f32_f16_e32 v105, v107
	v_sub_f32_e32 v18, v18, v105
	v_cvt_f32_f16_sdwa v105, v107 dst_sel:DWORD dst_unused:UNUSED_PAD src0_sel:WORD_1
	v_sub_f32_e32 v19, v19, v105
	v_cvt_pkrtz_f16_f32 v105, v18, v19
	ds_write2st64_b64 v179, v[106:107], v[104:105] offset1:64
	v_cndmask_b32_e64 v18, v123, v124, s[44:45]
	v_cndmask_b32_e64 v104, v131, v126, s[44:45]
	s_nop 0
	v_mov_b32_dpp v18, v18 quad_perm:[1,0,3,2] row_mask:0xf bank_mask:0xf bound_ctrl:1
	v_mov_b32_dpp v104, v104 quad_perm:[1,0,3,2] row_mask:0xf bank_mask:0xf bound_ctrl:1
	v_cndmask_b32_e64 v19, v18, v123, s[44:45]
	v_cndmask_b32_e64 v18, v124, v18, s[44:45]
	v_cndmask_b32_e64 v105, v104, v131, s[44:45]
	v_cndmask_b32_e64 v104, v126, v104, s[44:45]
	v_cndmask_b32_e64 v106, v19, v105, s[46:47]
	v_cndmask_b32_e64 v107, v18, v104, s[46:47]
	s_nop 0
	v_mov_b32_dpp v108, v106 quad_perm:[2,3,0,1] row_mask:0xf bank_mask:0xf bound_ctrl:1
	v_mov_b32_dpp v109, v107 quad_perm:[2,3,0,1] row_mask:0xf bank_mask:0xf bound_ctrl:1
	v_cndmask_b32_e64 v107, v104, v109, s[46:47]
	v_cndmask_b32_e64 v106, v105, v108, s[46:47]
	v_cndmask_b32_e64 v105, v109, v18, s[46:47]
	v_cndmask_b32_e64 v104, v108, v19, s[46:47]
	v_lshl_add_u64 v[18:19], v[164:165], 0, s[8:9]
	global_store_dwordx4 v[18:19], v[104:107], off
	v_cndmask_b32_e64 v18, v128, v130, s[44:45]
	s_nop 0
	v_cndmask_b32_e64 v104, v120, v110, s[44:45]
	v_mov_b32_dpp v18, v18 quad_perm:[1,0,3,2] row_mask:0xf bank_mask:0xf bound_ctrl:1
	v_cndmask_b32_e64 v19, v18, v128, s[44:45]
	v_mov_b32_dpp v104, v104 quad_perm:[1,0,3,2] row_mask:0xf bank_mask:0xf bound_ctrl:1
	v_cndmask_b32_e64 v18, v130, v18, s[44:45]
	v_cndmask_b32_e64 v105, v104, v120, s[44:45]
	v_cndmask_b32_e64 v104, v110, v104, s[44:45]
	v_cndmask_b32_e64 v106, v19, v105, s[46:47]
	v_cndmask_b32_e64 v107, v18, v104, s[46:47]
	s_nop 0
	v_mov_b32_dpp v108, v106 quad_perm:[2,3,0,1] row_mask:0xf bank_mask:0xf bound_ctrl:1
	v_mov_b32_dpp v109, v107 quad_perm:[2,3,0,1] row_mask:0xf bank_mask:0xf bound_ctrl:1
	v_cndmask_b32_e64 v107, v104, v109, s[46:47]
	v_cndmask_b32_e64 v106, v105, v108, s[46:47]
	v_cndmask_b32_e64 v105, v109, v18, s[46:47]
	v_cndmask_b32_e64 v104, v108, v19, s[46:47]
	v_lshl_add_u64 v[18:19], v[164:165], 0, s[2:3]
	global_store_dwordx4 v[18:19], v[104:107], off
	s_waitcnt lgkmcnt(0)
	s_barrier
; #define LAS __attribute__((address_space(3)))
; __device__ __forceinline__ void p_r2(const Args& a, LAS unsigned char* lds, volatile LAS unsigned* MISC, int l, int wg, int G, int wave, int lane, int tid) {
;     ...
;             __syncthreads();
;             f32x4 acc[2] = {(f32x4){0.f, 0.f, 0.f, 0.f}, (f32x4){0.f, 0.f, 0.f, 0.f}};
; #pragma unroll
;             for (int s = 0; s < 4; ++s) { const int off = fr * 2048 + (((4 * (4 * wave + s) + fq) ^ fr) << 4);
;                 const f16x8 ah = *(const LAS f16x8*)(lds + R2_UH + off), al = *(const LAS f16x8*)(lds + R2_UL + off);
; #pragma unroll
;                 for (int nt = 0; nt < 2; ++nt) { acc[nt] = __builtin_amdgcn_mfma_f32_16x16x32_f16(ah, bh[s][nt], acc[nt], 0, 0, 0); acc[nt] = __builtin_amdgcn_mfma_f32_16x16x32_f16(ah, bl[s][nt], acc[nt], 0, 0, 0);
;                     acc[nt] = __builtin_amdgcn_mfma_f32_16x16x32_f16(al, bh[s][nt], acc[nt], 0, 0, 0); } }
; #pragma unroll
;             for (int nt = 0; nt < 2; ++nt)
; #pragma unroll
;                 for (int r = 0; r < 4; ++r) PART[(wave * 16 + 4 * fq + r) * 32 + 16 * nt + fr] = acc[nt][r];
;             __syncthreads();
;             float sgm = rbias;
; #pragma unroll
;             for (int w = 0; w < 8; ++w) sgm += PART[(w * 16 + (tid >> 5)) * 32 + (tid & 31)];
;             { const int half = lane >> 5, ee = lane & 31; float lg = sgm;
;               int si[4]; float sv[4];
; #pragma unroll
;               for (int k = 0; k < 4; ++k) { float mx = row16_max(lg); mx = fmaxf(mx, __shfl_xor(mx, 16)); const unsigned long long bal = __ballot(lg == mx);
;                   const unsigned bits = half ? (unsigned)(bal >> 32) : (unsigned)bal; si[k] = __ffs((int)bits) - 1; sv[k] = mx; if (ee == si[k]) lg = -3.0e38f; }
;               const float e1 = ex2((sv[1] - sv[0]) * LOG2E), e2 = ex2((sv[2] - sv[0]) * LOG2E), e3 = ex2((sv[3] - sv[0]) * LOG2E), inv = 1.0f / (1.0f + e1 + e2 + e3);
;               if (ee == 0) { const int t = tb + 2 * wave + half;
;                   *(LAS v4i*)(lds + R2_TOP + (t - 256 * chunk) * 16) = (v4i){si[0], si[1], si[2], si[3]}; *(LAS f32x4*)(lds + R2_TOP + 4096 + (t - 256 * chunk) * 16) = (f32x4){inv, e1 * inv, e2 * inv, e3 * inv};
; #pragma unroll
;                   for (int k = 0; k < 4; ++k) __hip_atomic_fetch_add((LAS unsigned*)(MISC + MW_HIST + si[k]), 1u, __ATOMIC_RELAXED, __HIP_MEMORY_SCOPE_WORKGROUP); } }
	ds_read_b128 v[104:107], v180
	ds_read_b128 v[108:111], v180 offset:32768
	s_waitcnt lgkmcnt(1)
	v_mfma_f32_16x16x32_f16 v[112:115], v[104:107], v[0:3], 0
	v_mfma_f32_16x16x32_f16 v[116:119], v[104:107], v[8:11], 0
	v_mfma_f32_16x16x32_f16 v[112:115], v[104:107], v[4:7], v[112:115]
	v_mfma_f32_16x16x32_f16 v[104:107], v[104:107], v[12:15], v[116:119]
	s_waitcnt lgkmcnt(0)
	v_mfma_f32_16x16x32_f16 v[112:115], v[108:111], v[0:3], v[112:115]
	v_mfma_f32_16x16x32_f16 v[104:107], v[108:111], v[8:11], v[104:107]
	ds_read_b128 v[108:111], v181
	s_nop 1
	ds_read_b128 v[116:119], v181 offset:32768
	s_waitcnt lgkmcnt(1)
	v_mfma_f32_16x16x32_f16 v[112:115], v[108:111], v[20:23], v[112:115]
	v_mfma_f32_16x16x32_f16 v[104:107], v[108:111], v[28:31], v[104:107]
	v_mfma_f32_16x16x32_f16 v[112:115], v[108:111], v[24:27], v[112:115]
	v_mfma_f32_16x16x32_f16 v[104:107], v[108:111], v[32:35], v[104:107]
	s_waitcnt lgkmcnt(0)
	v_mfma_f32_16x16x32_f16 v[112:115], v[116:119], v[20:23], v[112:115]
	v_mfma_f32_16x16x32_f16 v[104:107], v[116:119], v[28:31], v[104:107]
	ds_read_b128 v[108:111], v182
	ds_read_b128 v[116:119], v182 offset:32768
	s_waitcnt lgkmcnt(1)
	v_mfma_f32_16x16x32_f16 v[112:115], v[108:111], v[36:39], v[112:115]
	v_mfma_f32_16x16x32_f16 v[104:107], v[108:111], v[44:47], v[104:107]
	v_mfma_f32_16x16x32_f16 v[112:115], v[108:111], v[40:43], v[112:115]
	v_mfma_f32_16x16x32_f16 v[104:107], v[108:111], v[48:51], v[104:107]
	s_waitcnt lgkmcnt(0)
	v_mfma_f32_16x16x32_f16 v[112:115], v[116:119], v[36:39], v[112:115]
	v_mfma_f32_16x16x32_f16 v[104:107], v[116:119], v[44:47], v[104:107]
	ds_read_b128 v[108:111], v183
	ds_read_b128 v[116:119], v183 offset:32768
	s_waitcnt lgkmcnt(1)
	v_mfma_f32_16x16x32_f16 v[112:115], v[108:111], v[52:55], v[112:115]
	v_mfma_f32_16x16x32_f16 v[104:107], v[108:111], v[60:63], v[104:107]
	v_mfma_f32_16x16x32_f16 v[112:115], v[108:111], v[56:59], v[112:115]
	v_mfma_f32_16x16x32_f16 v[104:107], v[108:111], v[68:71], v[104:107]
	s_waitcnt lgkmcnt(0)
	v_mfma_f32_16x16x32_f16 v[112:115], v[116:119], v[52:55], v[112:115]
	v_mfma_f32_16x16x32_f16 v[104:107], v[116:119], v[60:63], v[104:107]
	s_nop 7
	ds_write2_b32 v184, v112, v104 offset1:16
	ds_write2_b32 v184, v113, v105 offset0:32 offset1:48
	ds_write2_b32 v184, v114, v106 offset0:64 offset1:80
	ds_write2_b32 v184, v115, v107 offset0:96 offset1:112
	s_waitcnt lgkmcnt(0)
	s_barrier
	ds_read2st64_b32 v[18:19], v65 offset1:8
	ds_read2st64_b32 v[104:105], v65 offset0:16 offset1:24
	ds_read2st64_b32 v[106:107], v65 offset0:32 offset1:40
	ds_read2st64_b32 v[108:109], v65 offset0:48 offset1:56
	s_waitcnt lgkmcnt(3)
	v_add_f32_e32 v18, v167, v18
	v_add_f32_e32 v18, v18, v19
	s_waitcnt lgkmcnt(2)
	v_add_f32_e32 v18, v18, v104
	v_add_f32_e32 v18, v18, v105
	s_waitcnt lgkmcnt(1)
	v_add_f32_e32 v18, v18, v106
	v_add_f32_e32 v18, v18, v107
	s_waitcnt lgkmcnt(0)
	v_add_f32_e32 v18, v18, v108
	v_add_f32_e32 v19, v18, v109
	s_nop 1
	v_max_f32_dpp v18, v19, v19 quad_perm:[1,0,3,2] row_mask:0xf bank_mask:0xf bound_ctrl:1
	s_nop 1
	v_max_f32_dpp v18, v18, v18 quad_perm:[2,3,0,1] row_mask:0xf bank_mask:0xf bound_ctrl:1
	s_nop 1
	v_max_f32_dpp v18, v18, v18 row_half_mirror row_mask:0xf bank_mask:0xf bound_ctrl:1
	s_nop 1
	v_max_f32_dpp v18, v18, v18 row_mirror row_mask:0xf bank_mask:0xf bound_ctrl:1
	v_mov_b32_e32 v110, v18
	s_nop 1
	v_permlane16_swap_b32_e32 v110, v18
	v_max_f32_e32 v18, v18, v110
	v_cmp_eq_f32_e32 vcc, v19, v18
	s_nop 1
	v_lshrrev_b64 v[104:105], v166, vcc
	v_ffbl_b32_e32 v104, v104
	v_cmp_ne_u32_e32 vcc, v67, v104
	s_nop 1
	v_cndmask_b32_e32 v108, v233, v19, vcc
	s_nop 1
	v_max_f32_dpp v19, v108, v108 quad_perm:[1,0,3,2] row_mask:0xf bank_mask:0xf bound_ctrl:1
	s_nop 1
	v_max_f32_dpp v19, v19, v19 quad_perm:[2,3,0,1] row_mask:0xf bank_mask:0xf bound_ctrl:1
	s_nop 1
	v_max_f32_dpp v19, v19, v19 row_half_mirror row_mask:0xf bank_mask:0xf bound_ctrl:1
	s_nop 1
	v_max_f32_dpp v19, v19, v19 row_mirror row_mask:0xf bank_mask:0xf bound_ctrl:1
	v_mov_b32_e32 v110, v19
	s_nop 1
	v_permlane16_swap_b32_e32 v110, v19
	v_max_f32_e32 v19, v19, v110
	v_cmp_eq_f32_e32 vcc, v108, v19
	s_nop 1
	v_lshrrev_b64 v[106:107], v166, vcc
	v_ffbl_b32_e32 v105, v106
	v_cmp_ne_u32_e32 vcc, v67, v105
	s_nop 1
	v_cndmask_b32_e32 v109, v233, v108, vcc
	s_nop 1
	v_max_f32_dpp v108, v109, v109 quad_perm:[1,0,3,2] row_mask:0xf bank_mask:0xf bound_ctrl:1
	s_nop 1
	v_max_f32_dpp v108, v108, v108 quad_perm:[2,3,0,1] row_mask:0xf bank_mask:0xf bound_ctrl:1
	s_nop 1
	v_max_f32_dpp v108, v108, v108 row_half_mirror row_mask:0xf bank_mask:0xf bound_ctrl:1
	s_nop 1
	v_max_f32_dpp v108, v108, v108 row_mirror row_mask:0xf bank_mask:0xf bound_ctrl:1
	v_mov_b32_e32 v110, v108
	s_nop 1
	v_permlane16_swap_b32_e32 v110, v108
	v_max_f32_e32 v108, v108, v110
	v_cmp_eq_f32_e32 vcc, v109, v108
	s_nop 1
	v_lshrrev_b64 v[106:107], v166, vcc
	v_ffbl_b32_e32 v106, v106
	v_cmp_ne_u32_e32 vcc, v67, v106
	s_nop 1
	v_cndmask_b32_e32 v107, v233, v109, vcc
	s_nop 1
	v_max_f32_dpp v109, v107, v107 quad_perm:[1,0,3,2] row_mask:0xf bank_mask:0xf bound_ctrl:1
	s_nop 1
	v_max_f32_dpp v109, v109, v109 quad_perm:[2,3,0,1] row_mask:0xf bank_mask:0xf bound_ctrl:1
	s_nop 1
	v_max_f32_dpp v109, v109, v109 row_half_mirror row_mask:0xf bank_mask:0xf bound_ctrl:1
	s_nop 1
	v_max_f32_dpp v109, v109, v109 row_mirror row_mask:0xf bank_mask:0xf bound_ctrl:1
	v_mov_b32_e32 v110, v109
	s_nop 1
	v_permlane16_swap_b32_e32 v110, v109
	v_max_f32_e32 v109, v109, v110
	v_cmp_eq_f32_e32 vcc, v107, v109
	s_and_saveexec_b64 s[2:3], s[48:49]
	s_cbranch_execz .LBB0_823
	v_sub_f32_e32 v109, v109, v18
	v_sub_f32_e32 v108, v108, v18
	v_sub_f32_e32 v18, v19, v18
	v_lshrrev_b64 v[110:111], v166, vcc
	v_mul_f32_e32 v18, 0x3fb8aa3b, v18
	v_ffbl_b32_e32 v107, v110
	v_mul_f32_e32 v108, 0x3fb8aa3b, v108
	v_exp_f32_e32 v110, v18
	v_mul_f32_e32 v109, 0x3fb8aa3b, v109
	v_exp_f32_e32 v111, v108
	v_exp_f32_e32 v109, v109
	v_add_f32_e32 v18, 1.0, v110
	v_add_f32_e32 v18, v18, v111
	v_add_f32_e32 v18, v18, v109
	v_div_scale_f32 v19, s[8:9], v18, v18, 1.0
	v_rcp_f32_e32 v108, v19
	s_nop 0
	v_fma_f32 v112, -v19, v108, 1.0
	v_fmac_f32_e32 v108, v112, v108
	v_div_scale_f32 v112, vcc, 1.0, v18, 1.0
	v_mul_f32_e32 v113, v112, v108
	v_fma_f32 v114, -v19, v113, v112
	v_fmac_f32_e32 v113, v114, v108
	v_fma_f32 v19, -v19, v113, v112
	v_div_fmas_f32 v19, v19, v108, v113
	v_div_fixup_f32 v108, v19, v18, 1.0
	v_add_u32_e32 v18, 0xfffff000, v185
	ds_write_b128 v18, v[104:107]
	v_pk_mul_f32 v[18:19], v[110:111], v[108:109] op_sel_hi:[1,0]
	v_mul_f32_e32 v111, v109, v108
	v_mov_b32_e32 v109, v18
	v_mov_b32_e32 v110, v19
	ds_write_b128 v185, v[108:111]
	v_lshl_add_u32 v18, v104, 2, s26
	ds_add_u32 v18, v201
	v_lshl_add_u32 v18, v105, 2, s26
	ds_add_u32 v18, v201
	v_lshl_add_u32 v18, v106, 2, s26
	ds_add_u32 v18, v201
	v_lshl_add_u32 v18, v107, 2, s26
	ds_add_u32 v18, v201
	s_branch .LBB0_823

; #define PG8_LAS __attribute__((address_space(3)))
; __device__ __forceinline__ f32x2 swiglu2s(f32x2 g, f32x2 u, float os) {
;     g[0] = fminf(g[0], 7.0f); g[1] = fminf(g[1], 7.0f); u[0] = fminf(fmaxf(u[0], -7.0f), 7.0f); u[1] = fminf(fmaxf(u[1], -7.0f), 7.0f);
;     const f32x2 x = g * (f32x2){-1.702f * 1.44269504f, -1.702f * 1.44269504f};
;     f32x2 d; d[0] = __builtin_amdgcn_exp2f(x[0]); d[1] = __builtin_amdgcn_exp2f(x[1]); d = d + (f32x2){1.0f, 1.0f};
;     f32x2 r; r[0] = __builtin_amdgcn_rcpf(d[0]); r[1] = __builtin_amdgcn_rcpf(d[1]);
;     const f32x2 osv = {os, os};
;     return (g * r) * (u * osv + osv);
; }
;     __device__ __forceinline__ void operator()(const f32x4 (&acc)[2][2][4][2], const Unit& u, int wr, int wc, int fr, int fq, PG8_LAS unsigned char* lds) const {
;         int row0 = u.pm * BM + wr * 64 + fr; int col0 = u.pn * HALF + wc * 32 + 8 * fq;
;         asm volatile("" : "+v"(row0), "+v"(col0));
;         f32x4 bgv[2], buv[2];
; #pragma unroll
;         for (int n = 0; n < 2; ++n) { bgv[n] = *(const PG8_LAS f32x4*)(lds + BIAS_LDS_OFF + u.par * 1024 + (wc * 32 + 8 * fq + 4 * n) * 4); buv[n] = *(const PG8_LAS f32x4*)(lds + BIAS_LDS_OFF + u.par * 1024 + (HALF + wc * 32 + 8 * fq + 4 * n) * 4); }
;         const int odd = fq & 1; unsigned char* obase = O + (size_t)(row0 + odd * 16) * 1024 + (col0 - 8 * odd);
; #pragma unroll
;         for (int ai = 0; ai < 2; ++ai)
; #pragma unroll
;             for (int mp = 0; mp < 2; ++mp) { unsigned char* rowp = obase + (size_t)(ai * HALF + mp * 32) * 1024; u32x2 w[2];
; #pragma unroll
;                 for (int q = 0; q < 2; ++q) { const int m = 2 * mp + q;
;                     const f32x4 g0 = acc[ai][0][m][0] * in_scale + bgv[0], g1 = acc[ai][0][m][1] * in_scale + bgv[1], u0 = acc[ai][1][m][0] * in_scale + buv[0], u1 = acc[ai][1][m][1] * in_scale + buv[1];
;                     const f32x2 a0 = swiglu2s((f32x2){g0[0], g0[1]}, (f32x2){u0[0], u0[1]}, out_scale), a1 = swiglu2s((f32x2){g0[2], g0[3]}, (f32x2){u0[2], u0[3]}, out_scale);
;                     const f32x2 a2 = swiglu2s((f32x2){g1[0], g1[1]}, (f32x2){u1[0], u1[1]}, out_scale), a3 = swiglu2s((f32x2){g1[2], g1[3]}, (f32x2){u1[2], u1[3]}, out_scale);
;                     w[q].x = pk4_fp8(a0[0], a0[1], a1[0], a1[1]); w[q].y = pk4_fp8(a2[0], a2[1], a3[0], a3[1]); }
.LBB0_1020:
	v_lshl_add_u32 v18, s4, 8, v243
	v_lshl_or_b32 v20, s2, 7, v209
	v_lshl_add_u32 v0, s25, 10, v248
	v_add_u32_e32 v18, v18, v211
	v_ashrrev_i32_e32 v19, 31, v18
	v_readlane_b32 s2, v252, 29
	ds_read_b128 v[12:15], v0
	ds_read_b128 v[8:11], v0 offset:16
	ds_read_b128 v[4:7], v0 offset:512
	ds_read_b128 v[0:3], v0 offset:528
	v_lshlrev_b64 v[18:19], 10, v[18:19]
	v_readlane_b32 s3, v252, 30
	v_sub_u32_e32 v20, v20, v244
	v_ashrrev_i32_e32 v21, 31, v20
	v_lshl_add_u64 v[18:19], s[2:3], 0, v[18:19]
	v_lshl_add_u64 v[22:23], v[18:19], 0, v[20:21]
	s_waitcnt lgkmcnt(0)
	v_pk_fma_f32 v[20:21], v[192:193], s[0:1], v[12:13] op_sel_hi:[1,0,1]
	s_mov_b32 s4, 0xc01d265f
	v_min_f32_e32 v20, 0x40e00000, v20
	v_min_f32_e32 v21, 0x40e00000, v21
	v_pk_mul_f32 v[36:37], v[20:21], s[4:5] op_sel_hi:[1,0]
	v_pk_fma_f32 v[30:31], v[184:185], s[0:1], v[4:5] op_sel_hi:[1,0,1]
	v_exp_f32_e32 v36, v36
	v_exp_f32_e32 v37, v37
	s_mov_b32 s3, 0xc0e00000
	v_pk_fma_f32 v[18:19], v[194:195], s[0:1], v[14:15] op_sel_hi:[1,0,1]
	v_med3_f32 v30, v30, s3, v240
	v_pk_add_f32 v[36:37], v[36:37], 1.0 op_sel_hi:[1,0]
	v_med3_f32 v31, v31, s3, v240
	v_rcp_f32_e32 v36, v36
	v_rcp_f32_e32 v37, v37
	v_pk_fma_f32 v[30:31], v[30:31], 4.0, 4.0 op_sel_hi:[1,0,0]
	v_min_f32_e32 v18, 0x40e00000, v18
	v_min_f32_e32 v19, 0x40e00000, v19
	v_pk_mul_f32 v[20:21], v[20:21], v[36:37]
	v_pk_fma_f32 v[28:29], v[186:187], s[0:1], v[6:7] op_sel_hi:[1,0,1]
	v_pk_mul_f32 v[20:21], v[30:31], v[20:21]
	v_pk_mul_f32 v[30:31], v[18:19], s[4:5] op_sel_hi:[1,0]
	v_med3_f32 v28, v28, s3, v240
	v_exp_f32_e32 v30, v30
	v_exp_f32_e32 v31, v31
	v_med3_f32 v29, v29, s3, v240
	v_pk_fma_f32 v[26:27], v[188:189], s[0:1], v[8:9] op_sel_hi:[1,0,1]
	v_pk_fma_f32 v[28:29], v[28:29], 4.0, 4.0 op_sel_hi:[1,0,0]
	v_pk_add_f32 v[30:31], v[30:31], 1.0 op_sel_hi:[1,0]
	v_pk_fma_f32 v[34:35], v[180:181], s[0:1], v[0:1] op_sel_hi:[1,0,1]
	v_rcp_f32_e32 v30, v30
	v_rcp_f32_e32 v31, v31
	v_pk_fma_f32 v[24:25], v[190:191], s[0:1], v[10:11] op_sel_hi:[1,0,1]
	v_pk_fma_f32 v[32:33], v[182:183], s[0:1], v[2:3] op_sel_hi:[1,0,1]
	v_pk_fma_f32 v[36:37], v[164:165], s[0:1], v[0:1] op_sel_hi:[1,0,1]
	v_pk_mul_f32 v[18:19], v[18:19], v[30:31]
	s_mov_b32 s2, 0x8000
	v_pk_mul_f32 v[28:29], v[28:29], v[18:19]
	v_min_f32_e32 v18, 0x40e00000, v26
	v_min_f32_e32 v19, 0x40e00000, v27
	v_pk_mul_f32 v[30:31], v[18:19], s[4:5] op_sel_hi:[1,0]
	v_med3_f32 v26, v34, s3, v240
	v_exp_f32_e32 v30, v30
	v_exp_f32_e32 v31, v31
	v_med3_f32 v27, v35, s3, v240
	v_pk_fma_f32 v[26:27], v[26:27], 4.0, 4.0 op_sel_hi:[1,0,0]
	v_pk_fma_f32 v[34:35], v[166:167], s[0:1], v[2:3] op_sel_hi:[1,0,1]
	v_pk_add_f32 v[30:31], v[30:31], 1.0 op_sel_hi:[1,0]
	s_nop 0
	v_rcp_f32_e32 v30, v30
	v_rcp_f32_e32 v31, v31
	s_nop 0
	v_pk_mul_f32 v[18:19], v[18:19], v[30:31]
	s_nop 0
	v_pk_mul_f32 v[26:27], v[26:27], v[18:19]
	v_min_f32_e32 v18, 0x40e00000, v24
	v_min_f32_e32 v19, 0x40e00000, v25
	v_pk_mul_f32 v[30:31], v[18:19], s[4:5] op_sel_hi:[1,0]
	v_med3_f32 v24, v32, s3, v240
	v_exp_f32_e32 v30, v30
	v_exp_f32_e32 v31, v31
	v_med3_f32 v25, v33, s3, v240
	v_pk_fma_f32 v[24:25], v[24:25], 4.0, 4.0 op_sel_hi:[1,0,0]
	v_pk_fma_f32 v[32:33], v[168:169], s[0:1], v[4:5] op_sel_hi:[1,0,1]
	v_pk_add_f32 v[30:31], v[30:31], 1.0 op_sel_hi:[1,0]
	v_med3_f32 v32, v32, s3, v240
	v_rcp_f32_e32 v30, v30
	v_rcp_f32_e32 v31, v31
	v_med3_f32 v33, v33, s3, v240
	v_pk_fma_f32 v[32:33], v[32:33], 4.0, 4.0 op_sel_hi:[1,0,0]
	v_pk_mul_f32 v[18:19], v[18:19], v[30:31]
	s_nop 0
	v_pk_mul_f32 v[24:25], v[24:25], v[18:19]
	v_cvt_pk_fp8_f32 v19, v26, v27
	v_cvt_pk_fp8_f32 v18, v20, v21
	v_pk_fma_f32 v[20:21], v[178:179], s[0:1], v[14:15] op_sel_hi:[1,0,1]
	v_cvt_pk_fp8_f32 v19, v24, v25 op_sel:[0,0,1]
	v_pk_fma_f32 v[24:25], v[176:177], s[0:1], v[12:13] op_sel_hi:[1,0,1]
	v_min_f32_e32 v20, 0x40e00000, v20
	v_min_f32_e32 v24, 0x40e00000, v24
	v_min_f32_e32 v25, 0x40e00000, v25
	v_pk_mul_f32 v[38:39], v[24:25], s[4:5] op_sel_hi:[1,0]
	v_min_f32_e32 v21, 0x40e00000, v21
	v_exp_f32_e32 v38, v38
	v_exp_f32_e32 v39, v39
	v_pk_fma_f32 v[30:31], v[170:171], s[0:1], v[6:7] op_sel_hi:[1,0,1]
	v_cvt_pk_fp8_f32 v18, v28, v29 op_sel:[0,0,1]
	v_med3_f32 v30, v30, s3, v240
	v_pk_add_f32 v[38:39], v[38:39], 1.0 op_sel_hi:[1,0]
	v_med3_f32 v31, v31, s3, v240
	v_rcp_f32_e32 v38, v38
	v_rcp_f32_e32 v39, v39
	v_pk_fma_f32 v[28:29], v[172:173], s[0:1], v[8:9] op_sel_hi:[1,0,1]
	v_pk_fma_f32 v[30:31], v[30:31], 4.0, 4.0 op_sel_hi:[1,0,0]
	v_pk_fma_f32 v[26:27], v[174:175], s[0:1], v[10:11] op_sel_hi:[1,0,1]
	v_pk_mul_f32 v[24:25], v[24:25], v[38:39]
	s_nop 0
	v_pk_mul_f32 v[24:25], v[32:33], v[24:25]
	v_pk_mul_f32 v[32:33], v[20:21], s[4:5] op_sel_hi:[1,0]
	s_nop 0
	v_exp_f32_e32 v32, v32
	v_exp_f32_e32 v33, v33
	s_nop 0
	v_pk_add_f32 v[32:33], v[32:33], 1.0 op_sel_hi:[1,0]
	s_nop 0
	v_rcp_f32_e32 v32, v32
	v_rcp_f32_e32 v33, v33
	s_nop 0
	v_pk_mul_f32 v[20:21], v[20:21], v[32:33]
	s_nop 0
	v_pk_mul_f32 v[30:31], v[30:31], v[20:21]
	v_min_f32_e32 v20, 0x40e00000, v28
	v_min_f32_e32 v21, 0x40e00000, v29
	v_pk_mul_f32 v[32:33], v[20:21], s[4:5] op_sel_hi:[1,0]
	v_med3_f32 v28, v36, s3, v240
	v_exp_f32_e32 v32, v32
	v_exp_f32_e32 v33, v33
	v_med3_f32 v29, v37, s3, v240
	v_pk_fma_f32 v[28:29], v[28:29], 4.0, 4.0 op_sel_hi:[1,0,0]
	v_pk_add_f32 v[32:33], v[32:33], 1.0 op_sel_hi:[1,0]
	s_nop 0
	v_rcp_f32_e32 v32, v32
	v_rcp_f32_e32 v33, v33
	s_nop 0
	v_pk_mul_f32 v[20:21], v[20:21], v[32:33]
	s_nop 0
	v_pk_mul_f32 v[28:29], v[28:29], v[20:21]
	v_min_f32_e32 v20, 0x40e00000, v26
	v_min_f32_e32 v21, 0x40e00000, v27
	v_pk_mul_f32 v[32:33], v[20:21], s[4:5] op_sel_hi:[1,0]
	v_med3_f32 v26, v34, s3, v240
	v_exp_f32_e32 v32, v32
; __device__ __forceinline__ unsigned pk4_fp8(float a, float b, float c, float d) { int w = 0; w = __builtin_amdgcn_cvt_pk_fp8_f32(a, b, w, false); w = __builtin_amdgcn_cvt_pk_fp8_f32(c, d, w, true); return (unsigned)w; }
; __device__ __forceinline__ unsigned pk4_fp8(float a, float b, float c, float d) { int w = 0; w = __builtin_amdgcn_cvt_pk_fp8_f32(a, b, w, false); w = __builtin_amdgcn_cvt_pk_fp8_f32(c, d, w, true); return (unsigned)w; }
; __device__ __forceinline__ f32x2 swiglu2s(f32x2 g, f32x2 u, float os) {
;     g[0] = fminf(g[0], 7.0f); g[1] = fminf(g[1], 7.0f); u[0] = fminf(fmaxf(u[0], -7.0f), 7.0f); u[1] = fminf(fmaxf(u[1], -7.0f), 7.0f);
;     const f32x2 x = g * (f32x2){-1.702f * 1.44269504f, -1.702f * 1.44269504f};
;     f32x2 d; d[0] = __builtin_amdgcn_exp2f(x[0]); d[1] = __builtin_amdgcn_exp2f(x[1]); d = d + (f32x2){1.0f, 1.0f};
;     f32x2 r; r[0] = __builtin_amdgcn_rcpf(d[0]); r[1] = __builtin_amdgcn_rcpf(d[1]);
;     const f32x2 osv = {os, os};
;     return (g * r) * (u * osv + osv);
; }
;     __device__ __forceinline__ void operator()(const f32x4 (&acc)[2][2][4][2], const Unit& u, int wr, int wc, int fr, int fq, PG8_LAS unsigned char* lds) const {
;     ...
;             for (int mp = 0; mp < 2; ++mp) { unsigned char* rowp = obase + (size_t)(ai * HALF + mp * 32) * 1024; u32x2 w[2];
; #pragma unroll
;                 for (int q = 0; q < 2; ++q) { const int m = 2 * mp + q;
;                     const f32x4 g0 = acc[ai][0][m][0] * in_scale + bgv[0], g1 = acc[ai][0][m][1] * in_scale + bgv[1], u0 = acc[ai][1][m][0] * in_scale + buv[0], u1 = acc[ai][1][m][1] * in_scale + buv[1];
;                     const f32x2 a0 = swiglu2s((f32x2){g0[0], g0[1]}, (f32x2){u0[0], u0[1]}, out_scale), a1 = swiglu2s((f32x2){g0[2], g0[3]}, (f32x2){u0[2], u0[3]}, out_scale);
;                     const f32x2 a2 = swiglu2s((f32x2){g1[0], g1[1]}, (f32x2){u1[0], u1[1]}, out_scale), a3 = swiglu2s((f32x2){g1[2], g1[3]}, (f32x2){u1[2], u1[3]}, out_scale);
;                     w[q].x = pk4_fp8(a0[0], a0[1], a1[0], a1[1]); w[q].y = pk4_fp8(a2[0], a2[1], a3[0], a3[1]); }
;                 const auto sx = __builtin_amdgcn_permlane16_swap(w[0].x, w[1].x, false, false), sy = __builtin_amdgcn_permlane16_swap(w[0].y, w[1].y, false, false);
;                 u32x4 o; o.x = sx[0]; o.y = sy[0]; o.z = sx[1]; o.w = sy[1];
;                 *(u32x4*)rowp = o; }
	v_exp_f32_e32 v33, v33
	v_med3_f32 v27, v35, s3, v240
	v_pk_fma_f32 v[26:27], v[26:27], 4.0, 4.0 op_sel_hi:[1,0,0]
	v_pk_fma_f32 v[34:35], v[148:149], s[0:1], v[0:1] op_sel_hi:[1,0,1]
	v_pk_add_f32 v[32:33], v[32:33], 1.0 op_sel_hi:[1,0]
	s_nop 0
	v_rcp_f32_e32 v32, v32
	v_rcp_f32_e32 v33, v33
	s_nop 0
	v_pk_mul_f32 v[20:21], v[20:21], v[32:33]
	s_nop 0
	v_pk_mul_f32 v[26:27], v[26:27], v[20:21]
	v_cvt_pk_fp8_f32 v20, v24, v25
	v_cvt_pk_fp8_f32 v21, v28, v29
	v_pk_fma_f32 v[28:29], v[154:155], s[0:1], v[6:7] op_sel_hi:[1,0,1]
	v_pk_fma_f32 v[24:25], v[158:159], s[0:1], v[10:11] op_sel_hi:[1,0,1]
	v_cvt_pk_fp8_f32 v20, v30, v31 op_sel:[0,0,1]
	v_cvt_pk_fp8_f32 v21, v26, v27 op_sel:[0,0,1]
	v_pk_fma_f32 v[30:31], v[152:153], s[0:1], v[4:5] op_sel_hi:[1,0,1]
	v_med3_f32 v28, v28, s3, v240
	v_permlane16_swap_b32_e32 v18, v20
	v_permlane16_swap_b32_e32 v19, v21
	global_store_dwordx4 v[22:23], v[18:21], off
	v_med3_f32 v30, v30, s3, v240
	v_med3_f32 v31, v31, s3, v240
	v_pk_fma_f32 v[20:21], v[160:161], s[0:1], v[12:13] op_sel_hi:[1,0,1]
	v_pk_fma_f32 v[18:19], v[162:163], s[0:1], v[14:15] op_sel_hi:[1,0,1]
	v_min_f32_e32 v20, 0x40e00000, v20
	v_min_f32_e32 v21, 0x40e00000, v21
	v_pk_mul_f32 v[36:37], v[20:21], s[4:5] op_sel_hi:[1,0]
	v_pk_fma_f32 v[30:31], v[30:31], 4.0, 4.0 op_sel_hi:[1,0,0]
	v_exp_f32_e32 v36, v36
	v_exp_f32_e32 v37, v37
	v_min_f32_e32 v18, 0x40e00000, v18
	v_min_f32_e32 v19, 0x40e00000, v19
	v_med3_f32 v29, v29, s3, v240
	v_pk_add_f32 v[36:37], v[36:37], 1.0 op_sel_hi:[1,0]
	v_pk_fma_f32 v[26:27], v[156:157], s[0:1], v[8:9] op_sel_hi:[1,0,1]
	v_rcp_f32_e32 v36, v36
	v_rcp_f32_e32 v37, v37
	v_pk_fma_f32 v[28:29], v[28:29], 4.0, 4.0 op_sel_hi:[1,0,0]
	v_pk_fma_f32 v[32:33], v[150:151], s[0:1], v[2:3] op_sel_hi:[1,0,1]
	v_pk_mul_f32 v[20:21], v[20:21], v[36:37]
	s_nop 0
	v_pk_mul_f32 v[20:21], v[30:31], v[20:21]
	v_pk_mul_f32 v[30:31], v[18:19], s[4:5] op_sel_hi:[1,0]
	v_pk_fma_f32 v[36:37], v[132:133], s[0:1], v[0:1] op_sel_hi:[1,0,1]
	v_exp_f32_e32 v30, v30
	v_exp_f32_e32 v31, v31
	s_nop 0
	v_pk_add_f32 v[30:31], v[30:31], 1.0 op_sel_hi:[1,0]
	s_nop 0
	v_rcp_f32_e32 v30, v30
	v_rcp_f32_e32 v31, v31
	s_nop 0
	v_pk_mul_f32 v[18:19], v[18:19], v[30:31]
	s_nop 0
	v_pk_mul_f32 v[28:29], v[28:29], v[18:19]
	v_min_f32_e32 v18, 0x40e00000, v26
	v_min_f32_e32 v19, 0x40e00000, v27
	v_pk_mul_f32 v[30:31], v[18:19], s[4:5] op_sel_hi:[1,0]
	v_med3_f32 v26, v34, s3, v240
	v_exp_f32_e32 v30, v30
	v_exp_f32_e32 v31, v31
	v_med3_f32 v27, v35, s3, v240
	v_pk_fma_f32 v[26:27], v[26:27], 4.0, 4.0 op_sel_hi:[1,0,0]
	v_pk_fma_f32 v[34:35], v[134:135], s[0:1], v[2:3] op_sel_hi:[1,0,1]
	v_pk_add_f32 v[30:31], v[30:31], 1.0 op_sel_hi:[1,0]
	s_nop 0
	v_rcp_f32_e32 v30, v30
	v_rcp_f32_e32 v31, v31
	s_nop 0
	v_pk_mul_f32 v[18:19], v[18:19], v[30:31]
	s_nop 0
	v_pk_mul_f32 v[26:27], v[26:27], v[18:19]
	v_min_f32_e32 v18, 0x40e00000, v24
	v_min_f32_e32 v19, 0x40e00000, v25
	v_pk_mul_f32 v[30:31], v[18:19], s[4:5] op_sel_hi:[1,0]
	v_med3_f32 v24, v32, s3, v240
	v_exp_f32_e32 v30, v30
	v_exp_f32_e32 v31, v31
	v_med3_f32 v25, v33, s3, v240
	v_pk_fma_f32 v[24:25], v[24:25], 4.0, 4.0 op_sel_hi:[1,0,0]
	v_pk_fma_f32 v[32:33], v[136:137], s[0:1], v[4:5] op_sel_hi:[1,0,1]
	v_pk_add_f32 v[30:31], v[30:31], 1.0 op_sel_hi:[1,0]
	v_med3_f32 v32, v32, s3, v240
	v_rcp_f32_e32 v30, v30
	v_rcp_f32_e32 v31, v31
	v_med3_f32 v33, v33, s3, v240
	v_pk_fma_f32 v[32:33], v[32:33], 4.0, 4.0 op_sel_hi:[1,0,0]
	v_pk_mul_f32 v[18:19], v[18:19], v[30:31]
	s_nop 0
	v_pk_mul_f32 v[24:25], v[24:25], v[18:19]
	v_cvt_pk_fp8_f32 v19, v26, v27
	v_cvt_pk_fp8_f32 v18, v20, v21
	v_pk_fma_f32 v[20:21], v[146:147], s[0:1], v[14:15] op_sel_hi:[1,0,1]
	v_cvt_pk_fp8_f32 v19, v24, v25 op_sel:[0,0,1]
	v_pk_fma_f32 v[24:25], v[144:145], s[0:1], v[12:13] op_sel_hi:[1,0,1]
	v_min_f32_e32 v20, 0x40e00000, v20
	v_min_f32_e32 v24, 0x40e00000, v24
	v_min_f32_e32 v25, 0x40e00000, v25
	v_pk_mul_f32 v[38:39], v[24:25], s[4:5] op_sel_hi:[1,0]
	v_min_f32_e32 v21, 0x40e00000, v21
	v_exp_f32_e32 v38, v38
	v_exp_f32_e32 v39, v39
	v_pk_fma_f32 v[30:31], v[138:139], s[0:1], v[6:7] op_sel_hi:[1,0,1]
	v_cvt_pk_fp8_f32 v18, v28, v29 op_sel:[0,0,1]
	v_med3_f32 v30, v30, s3, v240
	v_pk_add_f32 v[38:39], v[38:39], 1.0 op_sel_hi:[1,0]
	v_med3_f32 v31, v31, s3, v240
	v_rcp_f32_e32 v38, v38
	v_rcp_f32_e32 v39, v39
	v_pk_fma_f32 v[28:29], v[140:141], s[0:1], v[8:9] op_sel_hi:[1,0,1]
	v_pk_fma_f32 v[30:31], v[30:31], 4.0, 4.0 op_sel_hi:[1,0,0]
	v_pk_fma_f32 v[26:27], v[142:143], s[0:1], v[10:11] op_sel_hi:[1,0,1]
	v_pk_mul_f32 v[24:25], v[24:25], v[38:39]
	s_nop 0
	v_pk_mul_f32 v[24:25], v[32:33], v[24:25]
	v_pk_mul_f32 v[32:33], v[20:21], s[4:5] op_sel_hi:[1,0]
	s_nop 0
	v_exp_f32_e32 v32, v32
	v_exp_f32_e32 v33, v33
	s_nop 0
	v_pk_add_f32 v[32:33], v[32:33], 1.0 op_sel_hi:[1,0]
	s_nop 0
	v_rcp_f32_e32 v32, v32
	v_rcp_f32_e32 v33, v33
	s_nop 0
	v_pk_mul_f32 v[20:21], v[20:21], v[32:33]
	s_nop 0
	v_pk_mul_f32 v[30:31], v[30:31], v[20:21]
	v_min_f32_e32 v20, 0x40e00000, v28
	v_min_f32_e32 v21, 0x40e00000, v29
	v_pk_mul_f32 v[32:33], v[20:21], s[4:5] op_sel_hi:[1,0]
	v_med3_f32 v28, v36, s3, v240
	v_exp_f32_e32 v32, v32
	v_exp_f32_e32 v33, v33
	v_med3_f32 v29, v37, s3, v240
	v_pk_fma_f32 v[28:29], v[28:29], 4.0, 4.0 op_sel_hi:[1,0,0]
	v_pk_add_f32 v[32:33], v[32:33], 1.0 op_sel_hi:[1,0]
	s_nop 0
	v_rcp_f32_e32 v32, v32
	v_rcp_f32_e32 v33, v33
	s_nop 0
	v_pk_mul_f32 v[20:21], v[20:21], v[32:33]
	s_nop 0
	v_pk_mul_f32 v[28:29], v[28:29], v[20:21]
	v_min_f32_e32 v20, 0x40e00000, v26
	v_min_f32_e32 v21, 0x40e00000, v27
	v_pk_mul_f32 v[32:33], v[20:21], s[4:5] op_sel_hi:[1,0]
	v_med3_f32 v26, v34, s3, v240
	v_exp_f32_e32 v32, v32
; __device__ __forceinline__ unsigned pk4_fp8(float a, float b, float c, float d) { int w = 0; w = __builtin_amdgcn_cvt_pk_fp8_f32(a, b, w, false); w = __builtin_amdgcn_cvt_pk_fp8_f32(c, d, w, true); return (unsigned)w; }
; __device__ __forceinline__ unsigned pk4_fp8(float a, float b, float c, float d) { int w = 0; w = __builtin_amdgcn_cvt_pk_fp8_f32(a, b, w, false); w = __builtin_amdgcn_cvt_pk_fp8_f32(c, d, w, true); return (unsigned)w; }
; __device__ __forceinline__ f32x2 swiglu2s(f32x2 g, f32x2 u, float os) {
;     g[0] = fminf(g[0], 7.0f); g[1] = fminf(g[1], 7.0f); u[0] = fminf(fmaxf(u[0], -7.0f), 7.0f); u[1] = fminf(fmaxf(u[1], -7.0f), 7.0f);
;     const f32x2 x = g * (f32x2){-1.702f * 1.44269504f, -1.702f * 1.44269504f};
;     f32x2 d; d[0] = __builtin_amdgcn_exp2f(x[0]); d[1] = __builtin_amdgcn_exp2f(x[1]); d = d + (f32x2){1.0f, 1.0f};
;     f32x2 r; r[0] = __builtin_amdgcn_rcpf(d[0]); r[1] = __builtin_amdgcn_rcpf(d[1]);
;     const f32x2 osv = {os, os};
;     return (g * r) * (u * osv + osv);
; }
;     __device__ __forceinline__ void operator()(const f32x4 (&acc)[2][2][4][2], const Unit& u, int wr, int wc, int fr, int fq, PG8_LAS unsigned char* lds) const {
;     ...
;             for (int mp = 0; mp < 2; ++mp) { unsigned char* rowp = obase + (size_t)(ai * HALF + mp * 32) * 1024; u32x2 w[2];
; #pragma unroll
;                 for (int q = 0; q < 2; ++q) { const int m = 2 * mp + q;
;                     const f32x4 g0 = acc[ai][0][m][0] * in_scale + bgv[0], g1 = acc[ai][0][m][1] * in_scale + bgv[1], u0 = acc[ai][1][m][0] * in_scale + buv[0], u1 = acc[ai][1][m][1] * in_scale + buv[1];
;                     const f32x2 a0 = swiglu2s((f32x2){g0[0], g0[1]}, (f32x2){u0[0], u0[1]}, out_scale), a1 = swiglu2s((f32x2){g0[2], g0[3]}, (f32x2){u0[2], u0[3]}, out_scale);
;                     const f32x2 a2 = swiglu2s((f32x2){g1[0], g1[1]}, (f32x2){u1[0], u1[1]}, out_scale), a3 = swiglu2s((f32x2){g1[2], g1[3]}, (f32x2){u1[2], u1[3]}, out_scale);
;                     w[q].x = pk4_fp8(a0[0], a0[1], a1[0], a1[1]); w[q].y = pk4_fp8(a2[0], a2[1], a3[0], a3[1]); }
;                 const auto sx = __builtin_amdgcn_permlane16_swap(w[0].x, w[1].x, false, false), sy = __builtin_amdgcn_permlane16_swap(w[0].y, w[1].y, false, false);
;                 u32x4 o; o.x = sx[0]; o.y = sy[0]; o.z = sx[1]; o.w = sy[1];
;                 *(u32x4*)rowp = o; }
	v_exp_f32_e32 v33, v33
	v_med3_f32 v27, v35, s3, v240
	v_pk_fma_f32 v[26:27], v[26:27], 4.0, 4.0 op_sel_hi:[1,0,0]
	v_pk_fma_f32 v[34:35], v[116:117], s[0:1], v[0:1] op_sel_hi:[1,0,1]
	v_pk_add_f32 v[32:33], v[32:33], 1.0 op_sel_hi:[1,0]
	s_nop 0
	v_rcp_f32_e32 v32, v32
	v_rcp_f32_e32 v33, v33
	s_nop 0
	v_pk_mul_f32 v[20:21], v[20:21], v[32:33]
	s_nop 0
	v_pk_mul_f32 v[26:27], v[26:27], v[20:21]
	v_cvt_pk_fp8_f32 v20, v24, v25
	v_cvt_pk_fp8_f32 v21, v28, v29
	v_add_co_u32_e32 v24, vcc, s2, v22
	v_cvt_pk_fp8_f32 v20, v30, v31 op_sel:[0,0,1]
	v_cvt_pk_fp8_f32 v21, v26, v27 op_sel:[0,0,1]
	v_addc_co_u32_e32 v25, vcc, 0, v23, vcc
	v_permlane16_swap_b32_e32 v18, v20
	v_permlane16_swap_b32_e32 v19, v21
	global_store_dwordx4 v[24:25], v[18:21], off
	v_pk_fma_f32 v[30:31], v[120:121], s[0:1], v[4:5] op_sel_hi:[1,0,1]
	v_pk_fma_f32 v[28:29], v[122:123], s[0:1], v[6:7] op_sel_hi:[1,0,1]
	v_pk_fma_f32 v[20:21], v[128:129], s[0:1], v[12:13] op_sel_hi:[1,0,1]
	v_pk_fma_f32 v[18:19], v[130:131], s[0:1], v[14:15] op_sel_hi:[1,0,1]
	v_min_f32_e32 v20, 0x40e00000, v20
	v_min_f32_e32 v21, 0x40e00000, v21
	v_pk_mul_f32 v[36:37], v[20:21], s[4:5] op_sel_hi:[1,0]
	v_med3_f32 v30, v30, s3, v240
	v_exp_f32_e32 v36, v36
	v_exp_f32_e32 v37, v37
	v_med3_f32 v31, v31, s3, v240
	v_pk_fma_f32 v[30:31], v[30:31], 4.0, 4.0 op_sel_hi:[1,0,0]
	v_min_f32_e32 v18, 0x40e00000, v18
	v_pk_add_f32 v[36:37], v[36:37], 1.0 op_sel_hi:[1,0]
	v_min_f32_e32 v19, 0x40e00000, v19
	v_rcp_f32_e32 v36, v36
	v_rcp_f32_e32 v37, v37
	v_med3_f32 v28, v28, s3, v240
	v_med3_f32 v29, v29, s3, v240
	v_pk_fma_f32 v[26:27], v[124:125], s[0:1], v[8:9] op_sel_hi:[1,0,1]
	v_pk_mul_f32 v[20:21], v[20:21], v[36:37]
	v_pk_fma_f32 v[28:29], v[28:29], 4.0, 4.0 op_sel_hi:[1,0,0]
	v_pk_mul_f32 v[20:21], v[30:31], v[20:21]
	v_pk_mul_f32 v[30:31], v[18:19], s[4:5] op_sel_hi:[1,0]
	v_pk_fma_f32 v[24:25], v[126:127], s[0:1], v[10:11] op_sel_hi:[1,0,1]
	v_exp_f32_e32 v30, v30
	v_exp_f32_e32 v31, v31
	v_pk_fma_f32 v[32:33], v[118:119], s[0:1], v[2:3] op_sel_hi:[1,0,1]
	v_pk_fma_f32 v[36:37], v[100:101], s[0:1], v[0:1] op_sel_hi:[1,0,1]
	s_mov_b32 s2, 0x20000
	v_pk_add_f32 v[30:31], v[30:31], 1.0 op_sel_hi:[1,0]
	s_nop 0
	v_rcp_f32_e32 v30, v30
	v_rcp_f32_e32 v31, v31
	s_nop 0
	v_pk_mul_f32 v[18:19], v[18:19], v[30:31]
	s_nop 0
	v_pk_mul_f32 v[28:29], v[28:29], v[18:19]
	v_min_f32_e32 v18, 0x40e00000, v26
	v_min_f32_e32 v19, 0x40e00000, v27
	v_pk_mul_f32 v[30:31], v[18:19], s[4:5] op_sel_hi:[1,0]
	v_med3_f32 v26, v34, s3, v240
	v_exp_f32_e32 v30, v30
	v_exp_f32_e32 v31, v31
	v_med3_f32 v27, v35, s3, v240
	v_pk_fma_f32 v[26:27], v[26:27], 4.0, 4.0 op_sel_hi:[1,0,0]
	v_pk_fma_f32 v[34:35], v[102:103], s[0:1], v[2:3] op_sel_hi:[1,0,1]
	v_pk_add_f32 v[30:31], v[30:31], 1.0 op_sel_hi:[1,0]
	s_nop 0
	v_rcp_f32_e32 v30, v30
	v_rcp_f32_e32 v31, v31
	s_nop 0
	v_pk_mul_f32 v[18:19], v[18:19], v[30:31]
	s_nop 0
	v_pk_mul_f32 v[26:27], v[26:27], v[18:19]
	v_min_f32_e32 v18, 0x40e00000, v24
	v_min_f32_e32 v19, 0x40e00000, v25
	v_pk_mul_f32 v[30:31], v[18:19], s[4:5] op_sel_hi:[1,0]
	v_med3_f32 v24, v32, s3, v240
	v_exp_f32_e32 v30, v30
	v_exp_f32_e32 v31, v31
	v_med3_f32 v25, v33, s3, v240
	v_pk_fma_f32 v[24:25], v[24:25], 4.0, 4.0 op_sel_hi:[1,0,0]
	v_pk_fma_f32 v[32:33], v[104:105], s[0:1], v[4:5] op_sel_hi:[1,0,1]
	v_pk_add_f32 v[30:31], v[30:31], 1.0 op_sel_hi:[1,0]
	v_med3_f32 v32, v32, s3, v240
	v_rcp_f32_e32 v30, v30
	v_rcp_f32_e32 v31, v31
	v_med3_f32 v33, v33, s3, v240
	v_pk_fma_f32 v[32:33], v[32:33], 4.0, 4.0 op_sel_hi:[1,0,0]
	v_pk_mul_f32 v[18:19], v[18:19], v[30:31]
	s_nop 0
	v_pk_mul_f32 v[24:25], v[24:25], v[18:19]
	v_cvt_pk_fp8_f32 v19, v26, v27
	v_cvt_pk_fp8_f32 v18, v20, v21
	v_pk_fma_f32 v[20:21], v[114:115], s[0:1], v[14:15] op_sel_hi:[1,0,1]
	v_cvt_pk_fp8_f32 v19, v24, v25 op_sel:[0,0,1]
	v_pk_fma_f32 v[24:25], v[112:113], s[0:1], v[12:13] op_sel_hi:[1,0,1]
	v_min_f32_e32 v20, 0x40e00000, v20
	v_min_f32_e32 v24, 0x40e00000, v24
	v_min_f32_e32 v25, 0x40e00000, v25
	v_pk_mul_f32 v[38:39], v[24:25], s[4:5] op_sel_hi:[1,0]
	v_min_f32_e32 v21, 0x40e00000, v21
	v_exp_f32_e32 v38, v38
	v_exp_f32_e32 v39, v39
	v_pk_fma_f32 v[30:31], v[106:107], s[0:1], v[6:7] op_sel_hi:[1,0,1]
	v_cvt_pk_fp8_f32 v18, v28, v29 op_sel:[0,0,1]
	v_med3_f32 v30, v30, s3, v240
	v_pk_add_f32 v[38:39], v[38:39], 1.0 op_sel_hi:[1,0]
	v_med3_f32 v31, v31, s3, v240
	v_rcp_f32_e32 v38, v38
	v_rcp_f32_e32 v39, v39
	v_pk_fma_f32 v[28:29], v[108:109], s[0:1], v[8:9] op_sel_hi:[1,0,1]
	v_pk_fma_f32 v[30:31], v[30:31], 4.0, 4.0 op_sel_hi:[1,0,0]
	v_pk_fma_f32 v[26:27], v[110:111], s[0:1], v[10:11] op_sel_hi:[1,0,1]
	v_pk_mul_f32 v[24:25], v[24:25], v[38:39]
	s_nop 0
	v_pk_mul_f32 v[24:25], v[32:33], v[24:25]
	v_pk_mul_f32 v[32:33], v[20:21], s[4:5] op_sel_hi:[1,0]
	s_nop 0
	v_exp_f32_e32 v32, v32
	v_exp_f32_e32 v33, v33
	s_nop 0
	v_pk_add_f32 v[32:33], v[32:33], 1.0 op_sel_hi:[1,0]
	s_nop 0
	v_rcp_f32_e32 v32, v32
	v_rcp_f32_e32 v33, v33
	s_nop 0
	v_pk_mul_f32 v[20:21], v[20:21], v[32:33]
	s_nop 0
	v_pk_mul_f32 v[30:31], v[30:31], v[20:21]
	v_min_f32_e32 v20, 0x40e00000, v28
	v_min_f32_e32 v21, 0x40e00000, v29
	v_pk_mul_f32 v[32:33], v[20:21], s[4:5] op_sel_hi:[1,0]
	v_med3_f32 v28, v36, s3, v240
	v_exp_f32_e32 v32, v32
	v_exp_f32_e32 v33, v33
	v_med3_f32 v29, v37, s3, v240
	v_pk_fma_f32 v[28:29], v[28:29], 4.0, 4.0 op_sel_hi:[1,0,0]
	v_pk_add_f32 v[32:33], v[32:33], 1.0 op_sel_hi:[1,0]
	s_nop 0
	v_rcp_f32_e32 v32, v32
	v_rcp_f32_e32 v33, v33
	s_nop 0
	v_pk_mul_f32 v[20:21], v[20:21], v[32:33]
	s_nop 0
	v_pk_mul_f32 v[28:29], v[28:29], v[20:21]
	v_min_f32_e32 v20, 0x40e00000, v26
	v_min_f32_e32 v21, 0x40e00000, v27
; #define PG8_LAS __attribute__((address_space(3)))
; __device__ __forceinline__ unsigned pk4_fp8(float a, float b, float c, float d) { int w = 0; w = __builtin_amdgcn_cvt_pk_fp8_f32(a, b, w, false); w = __builtin_amdgcn_cvt_pk_fp8_f32(c, d, w, true); return (unsigned)w; }
; __device__ __forceinline__ unsigned pk4_fp8(float a, float b, float c, float d) { int w = 0; w = __builtin_amdgcn_cvt_pk_fp8_f32(a, b, w, false); w = __builtin_amdgcn_cvt_pk_fp8_f32(c, d, w, true); return (unsigned)w; }
;     __device__ __forceinline__ void prefetch(const Unit& u, int wid, int lane, PG8_LAS unsigned char* lds) const {
;         if (wid == 0) __builtin_amdgcn_global_load_lds((const unsigned*)(b1 + (size_t)u.e * 2048 + (lane < 32 ? u.pn * HALF + 4 * lane : 1024 + u.pn * HALF + 4 * (lane - 32))), (PG8_LAS unsigned*)(lds + BIAS_LDS_OFF + u.par * 1024), 16, 0, 0); }
;     __device__ __forceinline__ void operator()(const f32x4 (&acc)[2][2][4][2], const Unit& u, int wr, int wc, int fr, int fq, PG8_LAS unsigned char* lds) const {
;     ...
;             for (int mp = 0; mp < 2; ++mp) { unsigned char* rowp = obase + (size_t)(ai * HALF + mp * 32) * 1024; u32x2 w[2];
; #pragma unroll
;                 for (int q = 0; q < 2; ++q) { const int m = 2 * mp + q;
;                     const f32x4 g0 = acc[ai][0][m][0] * in_scale + bgv[0], g1 = acc[ai][0][m][1] * in_scale + bgv[1], u0 = acc[ai][1][m][0] * in_scale + buv[0], u1 = acc[ai][1][m][1] * in_scale + buv[1];
;                     const f32x2 a0 = swiglu2s((f32x2){g0[0], g0[1]}, (f32x2){u0[0], u0[1]}, out_scale), a1 = swiglu2s((f32x2){g0[2], g0[3]}, (f32x2){u0[2], u0[3]}, out_scale);
;                     const f32x2 a2 = swiglu2s((f32x2){g1[0], g1[1]}, (f32x2){u1[0], u1[1]}, out_scale), a3 = swiglu2s((f32x2){g1[2], g1[3]}, (f32x2){u1[2], u1[3]}, out_scale);
;                     w[q].x = pk4_fp8(a0[0], a0[1], a1[0], a1[1]); w[q].y = pk4_fp8(a2[0], a2[1], a3[0], a3[1]); }
;                 const auto sx = __builtin_amdgcn_permlane16_swap(w[0].x, w[1].x, false, false), sy = __builtin_amdgcn_permlane16_swap(w[0].y, w[1].y, false, false);
;                 u32x4 o; o.x = sx[0]; o.y = sy[0]; o.z = sx[1]; o.w = sy[1];
;                 *(u32x4*)rowp = o; }
	v_pk_mul_f32 v[32:33], v[20:21], s[4:5] op_sel_hi:[1,0]
	v_med3_f32 v26, v34, s3, v240
	v_exp_f32_e32 v32, v32
	v_exp_f32_e32 v33, v33
	v_med3_f32 v27, v35, s3, v240
	v_pk_fma_f32 v[26:27], v[26:27], 4.0, 4.0 op_sel_hi:[1,0,0]
	v_pk_fma_f32 v[34:35], v[84:85], s[0:1], v[0:1] op_sel_hi:[1,0,1]
	v_pk_add_f32 v[32:33], v[32:33], 1.0 op_sel_hi:[1,0]
	v_pk_fma_f32 v[0:1], v[68:69], s[0:1], v[0:1] op_sel_hi:[1,0,1]
	v_rcp_f32_e32 v32, v32
	v_rcp_f32_e32 v33, v33
	v_med3_f32 v0, v0, s3, v240
	v_med3_f32 v1, v1, s3, v240
	v_pk_fma_f32 v[0:1], v[0:1], 4.0, 4.0 op_sel_hi:[1,0,0]
	v_pk_mul_f32 v[20:21], v[20:21], v[32:33]
	v_pk_fma_f32 v[32:33], v[86:87], s[0:1], v[2:3] op_sel_hi:[1,0,1]
	v_pk_mul_f32 v[26:27], v[26:27], v[20:21]
	v_cvt_pk_fp8_f32 v20, v24, v25
	v_cvt_pk_fp8_f32 v21, v28, v29
	v_add_co_u32_e32 v24, vcc, s2, v22
	v_cvt_pk_fp8_f32 v20, v30, v31 op_sel:[0,0,1]
	v_cvt_pk_fp8_f32 v21, v26, v27 op_sel:[0,0,1]
	v_addc_co_u32_e32 v25, vcc, 0, v23, vcc
	v_permlane16_swap_b32_e32 v18, v20
	v_permlane16_swap_b32_e32 v19, v21
	global_store_dwordx4 v[24:25], v[18:21], off
	v_pk_fma_f32 v[30:31], v[88:89], s[0:1], v[4:5] op_sel_hi:[1,0,1]
	v_pk_fma_f32 v[28:29], v[90:91], s[0:1], v[6:7] op_sel_hi:[1,0,1]
	v_pk_fma_f32 v[20:21], v[96:97], s[0:1], v[12:13] op_sel_hi:[1,0,1]
	v_pk_fma_f32 v[18:19], v[98:99], s[0:1], v[14:15] op_sel_hi:[1,0,1]
	v_min_f32_e32 v20, 0x40e00000, v20
	v_min_f32_e32 v21, 0x40e00000, v21
	v_pk_mul_f32 v[36:37], v[20:21], s[4:5] op_sel_hi:[1,0]
	v_med3_f32 v30, v30, s3, v240
	v_exp_f32_e32 v36, v36
	v_exp_f32_e32 v37, v37
	v_med3_f32 v31, v31, s3, v240
	v_pk_fma_f32 v[30:31], v[30:31], 4.0, 4.0 op_sel_hi:[1,0,0]
	v_min_f32_e32 v18, 0x40e00000, v18
	v_pk_add_f32 v[36:37], v[36:37], 1.0 op_sel_hi:[1,0]
	v_min_f32_e32 v19, 0x40e00000, v19
	v_rcp_f32_e32 v36, v36
	v_rcp_f32_e32 v37, v37
	v_med3_f32 v28, v28, s3, v240
	v_med3_f32 v29, v29, s3, v240
	v_pk_fma_f32 v[26:27], v[92:93], s[0:1], v[8:9] op_sel_hi:[1,0,1]
	v_pk_mul_f32 v[20:21], v[20:21], v[36:37]
	v_pk_fma_f32 v[28:29], v[28:29], 4.0, 4.0 op_sel_hi:[1,0,0]
	v_pk_mul_f32 v[20:21], v[30:31], v[20:21]
	v_pk_mul_f32 v[30:31], v[18:19], s[4:5] op_sel_hi:[1,0]
	v_pk_fma_f32 v[24:25], v[94:95], s[0:1], v[10:11] op_sel_hi:[1,0,1]
	v_exp_f32_e32 v30, v30
	v_exp_f32_e32 v31, v31
	v_pk_fma_f32 v[12:13], v[80:81], s[0:1], v[12:13] op_sel_hi:[1,0,1]
	v_pk_fma_f32 v[4:5], v[72:73], s[0:1], v[4:5] op_sel_hi:[1,0,1]
	v_min_f32_e32 v12, 0x40e00000, v12
	v_pk_add_f32 v[30:31], v[30:31], 1.0 op_sel_hi:[1,0]
	v_min_f32_e32 v13, 0x40e00000, v13
	v_rcp_f32_e32 v30, v30
	v_rcp_f32_e32 v31, v31
	v_med3_f32 v4, v4, s3, v240
	v_med3_f32 v5, v5, s3, v240
	v_pk_fma_f32 v[14:15], v[82:83], s[0:1], v[14:15] op_sel_hi:[1,0,1]
	v_pk_mul_f32 v[18:19], v[18:19], v[30:31]
	v_pk_fma_f32 v[4:5], v[4:5], 4.0, 4.0 op_sel_hi:[1,0,0]
	v_pk_mul_f32 v[28:29], v[28:29], v[18:19]
	v_min_f32_e32 v18, 0x40e00000, v26
	v_min_f32_e32 v19, 0x40e00000, v27
	v_pk_mul_f32 v[30:31], v[18:19], s[4:5] op_sel_hi:[1,0]
	v_med3_f32 v26, v34, s3, v240
	v_exp_f32_e32 v30, v30
	v_exp_f32_e32 v31, v31
	v_med3_f32 v27, v35, s3, v240
	v_pk_fma_f32 v[26:27], v[26:27], 4.0, 4.0 op_sel_hi:[1,0,0]
	v_pk_fma_f32 v[6:7], v[74:75], s[0:1], v[6:7] op_sel_hi:[1,0,1]
	v_pk_add_f32 v[30:31], v[30:31], 1.0 op_sel_hi:[1,0]
	v_pk_fma_f32 v[8:9], v[76:77], s[0:1], v[8:9] op_sel_hi:[1,0,1]
	v_rcp_f32_e32 v30, v30
	v_rcp_f32_e32 v31, v31
	v_med3_f32 v6, v6, s3, v240
	v_med3_f32 v7, v7, s3, v240
	v_pk_fma_f32 v[6:7], v[6:7], 4.0, 4.0 op_sel_hi:[1,0,0]
	v_pk_mul_f32 v[18:19], v[18:19], v[30:31]
	v_min_f32_e32 v8, 0x40e00000, v8
	v_pk_mul_f32 v[26:27], v[26:27], v[18:19]
	v_min_f32_e32 v18, 0x40e00000, v24
	v_min_f32_e32 v19, 0x40e00000, v25
	v_pk_mul_f32 v[30:31], v[18:19], s[4:5] op_sel_hi:[1,0]
	v_med3_f32 v24, v32, s3, v240
	v_exp_f32_e32 v30, v30
	v_exp_f32_e32 v31, v31
	v_med3_f32 v25, v33, s3, v240
	v_pk_fma_f32 v[24:25], v[24:25], 4.0, 4.0 op_sel_hi:[1,0,0]
	v_min_f32_e32 v9, 0x40e00000, v9
	v_pk_add_f32 v[30:31], v[30:31], 1.0 op_sel_hi:[1,0]
	v_pk_fma_f32 v[10:11], v[78:79], s[0:1], v[10:11] op_sel_hi:[1,0,1]
	v_rcp_f32_e32 v30, v30
	v_rcp_f32_e32 v31, v31
	v_pk_fma_f32 v[2:3], v[70:71], s[0:1], v[2:3] op_sel_hi:[1,0,1]
	v_pk_mul_f32 v[18:19], v[18:19], v[30:31]
	s_nop 0
	v_pk_mul_f32 v[24:25], v[24:25], v[18:19]
	v_cvt_pk_fp8_f32 v18, v20, v21
	v_pk_mul_f32 v[20:21], v[12:13], s[4:5] op_sel_hi:[1,0]
	v_exp_f32_e32 v20, v20
	v_exp_f32_e32 v21, v21
	v_cvt_pk_fp8_f32 v19, v26, v27
	v_med3_f32 v2, v2, s3, v240
	v_med3_f32 v3, v3, s3, v240
	v_pk_add_f32 v[20:21], v[20:21], 1.0 op_sel_hi:[1,0]
	v_pk_fma_f32 v[2:3], v[2:3], 4.0, 4.0 op_sel_hi:[1,0,0]
	v_rcp_f32_e32 v20, v20
	v_rcp_f32_e32 v21, v21
	v_cvt_pk_fp8_f32 v18, v28, v29 op_sel:[0,0,1]
	v_cvt_pk_fp8_f32 v19, v24, v25 op_sel:[0,0,1]
	s_mov_b64 s[2:3], -1
	v_pk_mul_f32 v[12:13], v[12:13], v[20:21]
	v_pk_mul_f32 v[4:5], v[4:5], v[12:13]
	v_min_f32_e32 v12, 0x40e00000, v14
	v_min_f32_e32 v13, 0x40e00000, v15
	v_pk_mul_f32 v[14:15], v[12:13], s[4:5] op_sel_hi:[1,0]
	v_exp_f32_e32 v14, v14
	v_exp_f32_e32 v15, v15
	v_cvt_pk_fp8_f32 v20, v4, v5
	v_pk_add_f32 v[14:15], v[14:15], 1.0 op_sel_hi:[1,0]
	s_nop 0
	v_rcp_f32_e32 v14, v14
	v_rcp_f32_e32 v15, v15
	s_nop 0
	v_pk_mul_f32 v[12:13], v[12:13], v[14:15]
	s_nop 0
	v_pk_mul_f32 v[6:7], v[6:7], v[12:13]
	v_pk_mul_f32 v[12:13], v[8:9], s[4:5] op_sel_hi:[1,0]
	v_cvt_pk_fp8_f32 v20, v6, v7 op_sel:[0,0,1]
	v_exp_f32_e32 v12, v12
	v_exp_f32_e32 v13, v13
	v_permlane16_swap_b32_e32 v18, v20
	v_pk_add_f32 v[12:13], v[12:13], 1.0 op_sel_hi:[1,0]
	s_nop 0
	v_rcp_f32_e32 v12, v12
	v_rcp_f32_e32 v13, v13
	s_nop 0
	v_pk_mul_f32 v[8:9], v[8:9], v[12:13]
	s_nop 0
	v_pk_mul_f32 v[0:1], v[0:1], v[8:9]
	v_min_f32_e32 v8, 0x40e00000, v10
	v_min_f32_e32 v9, 0x40e00000, v11
	v_pk_mul_f32 v[10:11], v[8:9], s[4:5] op_sel_hi:[1,0]
	v_cvt_pk_fp8_f32 v21, v0, v1
	v_exp_f32_e32 v10, v10
	v_exp_f32_e32 v11, v11
	v_add_co_u32_e32 v0, vcc, 0x28000, v22
	v_pk_add_f32 v[10:11], v[10:11], 1.0 op_sel_hi:[1,0]
	s_nop 0
	v_rcp_f32_e32 v10, v10
	v_rcp_f32_e32 v11, v11
	v_addc_co_u32_e32 v1, vcc, 0, v23, vcc
	s_and_b64 vcc, exec, s[42:43]
	v_pk_mul_f32 v[8:9], v[8:9], v[10:11]
	s_nop 0
	v_pk_mul_f32 v[2:3], v[2:3], v[8:9]
	s_nop 0
	v_cvt_pk_fp8_f32 v21, v2, v3 op_sel:[0,0,1]
	s_nop 1
	v_permlane16_swap_b32_e32 v19, v21
	global_store_dwordx4 v[0:1], v[18:21], off
	s_cbranch_vccnz .LBB0_995
	s_andn2_b64 vcc, exec, s[46:47]
	s_and_b32 s25, s90, 1
	s_cbranch_vccnz .LBB0_1023
	s_lshl_b64 s[2:3], s[56:57], 13
	s_add_u32 s2, s72, s2
	s_addc_u32 s3, s73, s3
	s_lshl_b32 s4, s52, 7
	v_or_b32_e32 v0, s4, v17
	v_add_u32_e32 v1, s4, v245
	v_cndmask_b32_e64 v0, v1, v0, s[40:41]
	v_ashrrev_i32_e32 v1, 31, v0
	v_lshl_add_u64 v[0:1], v[0:1], 2, s[2:3]
	s_lshl_b32 s2, s25, 10
	s_add_i32 s2, s2, 0
	s_add_i32 m0, s2, 0x21400
	s_nop 0
	global_load_lds_dwordx4 v[0:1], off

; #define PG8_LAS __attribute__((address_space(3)))
; __device__ __forceinline__ unsigned pk4_fp8(float a, float b, float c, float d) { int w = 0; w = __builtin_amdgcn_cvt_pk_fp8_f32(a, b, w, false); w = __builtin_amdgcn_cvt_pk_fp8_f32(c, d, w, true); return (unsigned)w; }
; __device__ __forceinline__ unsigned pk4_fp8(float a, float b, float c, float d) { int w = 0; w = __builtin_amdgcn_cvt_pk_fp8_f32(a, b, w, false); w = __builtin_amdgcn_cvt_pk_fp8_f32(c, d, w, true); return (unsigned)w; }
;     __device__ __forceinline__ void operator()(const f32x4 (&acc)[2][2][4][2], const Unit& u, int wr, int wc, int fr, int fq, PG8_LAS unsigned char* lds) const {
;         int row0 = u.pm * BM + wr * 64 + fr; int col0 = u.pn * BM + wc * 32 + 8 * fq;
;         asm volatile("" : "+v"(row0), "+v"(col0));
;         f32x4 bv[2][2];
; #pragma unroll
;         for (int bj = 0; bj < 2; ++bj)
; #pragma unroll
;             for (int n = 0; n < 2; ++n) bv[bj][n] = *(const PG8_LAS f32x4*)(lds + BIAS_LDS_OFF + u.par * 1024 + (wc * 32 + 8 * fq + bj * HALF + 4 * n) * 4) * out_scale;
;         const float sc = scale * out_scale;
;         const int odd = fq & 1; unsigned char* obase = O + (size_t)(row0 + odd * 16) * ldc + (col0 - 8 * odd);
; #pragma unroll
;         for (int ai = 0; ai < 2; ++ai)
; #pragma unroll
;             for (int mp = 0; mp < 2; ++mp) { unsigned char* rowp = obase + (size_t)(ai * HALF + mp * 32) * ldc;
; #pragma unroll
;                 for (int bj = 0; bj < 2; ++bj) { u32x2 w[2];
; #pragma unroll
;                     for (int q = 0; q < 2; ++q) { const int m = 2 * mp + q; const f32x4 v0 = acc[ai][bj][m][0] * sc + bv[bj][0], v1 = acc[ai][bj][m][1] * sc + bv[bj][1];
;                         w[q].x = pk4_fp8(v0[0], v0[1], v0[2], v0[3]); w[q].y = pk4_fp8(v1[0], v1[1], v1[2], v1[3]); }
;                     const auto sx = __builtin_amdgcn_permlane16_swap(w[0].x, w[1].x, false, false), sy = __builtin_amdgcn_permlane16_swap(w[0].y, w[1].y, false, false);
;                     u32x4 o; o.x = sx[0]; o.y = sy[0]; o.z = sx[1]; o.w = sy[1];
;                     *(u32x4*)(rowp + bj * HALF) = o; } }
.LBB0_1126:
	v_lshl_add_u32 v18, s56, 8, v17
	v_lshl_or_b32 v20, s2, 8, v67
	v_lshl_add_u32 v19, s90, 10, v231
	ds_read_b128 v[0:3], v19
	ds_read_b128 v[4:7], v19 offset:16
	s_mov_b32 s2, 0x42000000
	v_add_u32_e32 v18, v18, v226
	v_sub_u32_e32 v20, v20, v227
	s_waitcnt lgkmcnt(0)
	v_pk_mul_f32 v[14:15], v[2:3], s[2:3] op_sel_hi:[1,0]
	v_pk_mul_f32 v[10:11], v[0:1], s[2:3] op_sel_hi:[1,0]
	v_pk_mul_f32 v[12:13], v[6:7], s[2:3] op_sel_hi:[1,0]
	v_pk_mul_f32 v[8:9], v[4:5], s[2:3] op_sel_hi:[1,0]
	ds_read_b128 v[0:3], v19 offset:512
	ds_read_b128 v[4:7], v19 offset:528
	v_ashrrev_i32_e32 v19, 31, v18
	v_lshlrev_b64 v[18:19], 10, v[18:19]
	v_ashrrev_i32_e32 v21, 31, v20
	s_waitcnt lgkmcnt(0)
	v_pk_mul_f32 v[2:3], v[2:3], s[2:3] op_sel_hi:[1,0]
	v_pk_mul_f32 v[0:1], v[0:1], s[2:3] op_sel_hi:[1,0]
	v_pk_mul_f32 v[6:7], v[6:7], s[2:3] op_sel_hi:[1,0]
	v_pk_mul_f32 v[4:5], v[4:5], s[2:3] op_sel_hi:[1,0]
	v_readlane_b32 s2, v252, 33
	v_readlane_b32 s3, v252, 34
	s_mov_b32 s40, 0x3e000000
	v_pk_fma_f32 v[24:25], v[192:193], s[40:41], v[10:11] op_sel_hi:[1,0,1]
	v_lshl_add_u64 v[18:19], s[2:3], 0, v[18:19]
	v_lshl_add_u64 v[18:19], v[18:19], 0, v[20:21]
	v_pk_fma_f32 v[28:29], v[188:189], s[40:41], v[8:9] op_sel_hi:[1,0,1]
	v_cvt_pk_fp8_f32 v20, v24, v25
	v_cvt_pk_fp8_f32 v21, v28, v29
	v_pk_fma_f32 v[22:23], v[194:195], s[40:41], v[14:15] op_sel_hi:[1,0,1]
	v_pk_fma_f32 v[26:27], v[190:191], s[40:41], v[12:13] op_sel_hi:[1,0,1]
	v_cvt_pk_fp8_f32 v20, v22, v23 op_sel:[0,0,1]
	v_cvt_pk_fp8_f32 v21, v26, v27 op_sel:[0,0,1]
	v_pk_fma_f32 v[26:27], v[184:185], s[40:41], v[10:11] op_sel_hi:[1,0,1]
	v_pk_fma_f32 v[30:31], v[180:181], s[40:41], v[8:9] op_sel_hi:[1,0,1]
	v_cvt_pk_fp8_f32 v22, v26, v27
	v_cvt_pk_fp8_f32 v23, v30, v31
	v_pk_fma_f32 v[24:25], v[186:187], s[40:41], v[14:15] op_sel_hi:[1,0,1]
	v_pk_fma_f32 v[28:29], v[182:183], s[40:41], v[12:13] op_sel_hi:[1,0,1]
	v_cvt_pk_fp8_f32 v22, v24, v25 op_sel:[0,0,1]
	v_cvt_pk_fp8_f32 v23, v28, v29 op_sel:[0,0,1]
	v_pk_fma_f32 v[24:25], v[176:177], s[40:41], v[0:1] op_sel_hi:[1,0,1]
	v_pk_fma_f32 v[28:29], v[172:173], s[40:41], v[4:5] op_sel_hi:[1,0,1]
	v_permlane16_swap_b32_e32 v20, v22
	v_permlane16_swap_b32_e32 v21, v23
	global_store_dwordx4 v[18:19], v[20:23], off
	v_pk_fma_f32 v[26:27], v[174:175], s[40:41], v[6:7] op_sel_hi:[1,0,1]
	v_pk_fma_f32 v[30:31], v[164:165], s[40:41], v[4:5] op_sel_hi:[1,0,1]
	v_cvt_pk_fp8_f32 v20, v24, v25
	v_cvt_pk_fp8_f32 v21, v28, v29
	v_pk_fma_f32 v[22:23], v[178:179], s[40:41], v[2:3] op_sel_hi:[1,0,1]
	v_pk_fma_f32 v[24:25], v[170:171], s[40:41], v[2:3] op_sel_hi:[1,0,1]
	v_cvt_pk_fp8_f32 v20, v22, v23 op_sel:[0,0,1]
	v_cvt_pk_fp8_f32 v21, v26, v27 op_sel:[0,0,1]
	v_pk_fma_f32 v[26:27], v[168:169], s[40:41], v[0:1] op_sel_hi:[1,0,1]
	v_cvt_pk_fp8_f32 v22, v26, v27
	v_cvt_pk_fp8_f32 v23, v30, v31
	v_pk_fma_f32 v[28:29], v[166:167], s[40:41], v[6:7] op_sel_hi:[1,0,1]
	v_pk_fma_f32 v[26:27], v[158:159], s[40:41], v[12:13] op_sel_hi:[1,0,1]
	v_cvt_pk_fp8_f32 v22, v24, v25 op_sel:[0,0,1]
	v_cvt_pk_fp8_f32 v23, v28, v29 op_sel:[0,0,1]
	v_pk_fma_f32 v[24:25], v[160:161], s[40:41], v[10:11] op_sel_hi:[1,0,1]
	v_pk_fma_f32 v[28:29], v[156:157], s[40:41], v[8:9] op_sel_hi:[1,0,1]
	v_permlane16_swap_b32_e32 v20, v22
	v_permlane16_swap_b32_e32 v21, v23
	global_store_dwordx4 v[18:19], v[20:23], off offset:128
	v_pk_fma_f32 v[30:31], v[148:149], s[40:41], v[8:9] op_sel_hi:[1,0,1]
	s_mov_b32 s2, 0x8000
	v_cvt_pk_fp8_f32 v20, v24, v25
	v_cvt_pk_fp8_f32 v21, v28, v29
	v_pk_fma_f32 v[22:23], v[162:163], s[40:41], v[14:15] op_sel_hi:[1,0,1]
	v_pk_fma_f32 v[24:25], v[154:155], s[40:41], v[14:15] op_sel_hi:[1,0,1]
	v_cvt_pk_fp8_f32 v20, v22, v23 op_sel:[0,0,1]
	v_cvt_pk_fp8_f32 v21, v26, v27 op_sel:[0,0,1]
	v_pk_fma_f32 v[26:27], v[152:153], s[40:41], v[10:11] op_sel_hi:[1,0,1]
	v_cvt_pk_fp8_f32 v22, v26, v27
	v_cvt_pk_fp8_f32 v23, v30, v31
	v_pk_fma_f32 v[28:29], v[150:151], s[40:41], v[12:13] op_sel_hi:[1,0,1]
	v_pk_fma_f32 v[26:27], v[144:145], s[40:41], v[0:1] op_sel_hi:[1,0,1]
	v_cvt_pk_fp8_f32 v22, v24, v25 op_sel:[0,0,1]
	v_cvt_pk_fp8_f32 v23, v28, v29 op_sel:[0,0,1]
	v_add_co_u32_e32 v24, vcc, s2, v18
	v_permlane16_swap_b32_e32 v20, v22
	v_permlane16_swap_b32_e32 v21, v23
	v_addc_co_u32_e32 v25, vcc, 0, v19, vcc
	global_store_dwordx4 v[24:25], v[20:23], off
	v_pk_fma_f32 v[30:31], v[140:141], s[40:41], v[4:5] op_sel_hi:[1,0,1]
	v_pk_fma_f32 v[28:29], v[142:143], s[40:41], v[6:7] op_sel_hi:[1,0,1]
	v_cvt_pk_fp8_f32 v20, v26, v27
	v_cvt_pk_fp8_f32 v21, v30, v31
	v_pk_fma_f32 v[22:23], v[146:147], s[40:41], v[2:3] op_sel_hi:[1,0,1]
	v_pk_fma_f32 v[32:33], v[132:133], s[40:41], v[4:5] op_sel_hi:[1,0,1]
	v_cvt_pk_fp8_f32 v20, v22, v23 op_sel:[0,0,1]
	v_cvt_pk_fp8_f32 v21, v28, v29 op_sel:[0,0,1]
	v_pk_fma_f32 v[28:29], v[136:137], s[40:41], v[0:1] op_sel_hi:[1,0,1]
	v_cvt_pk_fp8_f32 v22, v28, v29
	v_cvt_pk_fp8_f32 v23, v32, v33
	v_pk_fma_f32 v[26:27], v[138:139], s[40:41], v[2:3] op_sel_hi:[1,0,1]
; #define PG8_LAS __attribute__((address_space(3)))
; __device__ __forceinline__ unsigned pk4_fp8(float a, float b, float c, float d) { int w = 0; w = __builtin_amdgcn_cvt_pk_fp8_f32(a, b, w, false); w = __builtin_amdgcn_cvt_pk_fp8_f32(c, d, w, true); return (unsigned)w; }
; __device__ __forceinline__ unsigned pk4_fp8(float a, float b, float c, float d) { int w = 0; w = __builtin_amdgcn_cvt_pk_fp8_f32(a, b, w, false); w = __builtin_amdgcn_cvt_pk_fp8_f32(c, d, w, true); return (unsigned)w; }
;     __device__ __forceinline__ void prefetch(const Unit& u, int wid, int lane, PG8_LAS unsigned char* lds) const {
;         if (wid == 0) __builtin_amdgcn_global_load_lds((const unsigned*)(bias + (size_t)u.e * bias_stride + u.pn * BM + 4 * lane), (PG8_LAS unsigned*)(lds + BIAS_LDS_OFF + u.par * 1024), 16, 0, 0); }
;     __device__ __forceinline__ void operator()(const f32x4 (&acc)[2][2][4][2], const Unit& u, int wr, int wc, int fr, int fq, PG8_LAS unsigned char* lds) const {
;     ...
;             for (int mp = 0; mp < 2; ++mp) { unsigned char* rowp = obase + (size_t)(ai * HALF + mp * 32) * ldc;
; #pragma unroll
;                 for (int bj = 0; bj < 2; ++bj) { u32x2 w[2];
; #pragma unroll
;                     for (int q = 0; q < 2; ++q) { const int m = 2 * mp + q; const f32x4 v0 = acc[ai][bj][m][0] * sc + bv[bj][0], v1 = acc[ai][bj][m][1] * sc + bv[bj][1];
;                         w[q].x = pk4_fp8(v0[0], v0[1], v0[2], v0[3]); w[q].y = pk4_fp8(v1[0], v1[1], v1[2], v1[3]); }
;                     const auto sx = __builtin_amdgcn_permlane16_swap(w[0].x, w[1].x, false, false), sy = __builtin_amdgcn_permlane16_swap(w[0].y, w[1].y, false, false);
;                     u32x4 o; o.x = sx[0]; o.y = sy[0]; o.z = sx[1]; o.w = sy[1];
;                     *(u32x4*)(rowp + bj * HALF) = o; } }
	v_pk_fma_f32 v[30:31], v[134:135], s[40:41], v[6:7] op_sel_hi:[1,0,1]
	v_cvt_pk_fp8_f32 v22, v26, v27 op_sel:[0,0,1]
	v_cvt_pk_fp8_f32 v23, v30, v31 op_sel:[0,0,1]
	v_pk_fma_f32 v[28:29], v[124:125], s[40:41], v[8:9] op_sel_hi:[1,0,1]
	v_pk_fma_f32 v[26:27], v[126:127], s[40:41], v[12:13] op_sel_hi:[1,0,1]
	v_permlane16_swap_b32_e32 v20, v22
	v_permlane16_swap_b32_e32 v21, v23
	global_store_dwordx4 v[24:25], v[20:23], off offset:128
	v_pk_fma_f32 v[24:25], v[128:129], s[40:41], v[10:11] op_sel_hi:[1,0,1]
	v_pk_fma_f32 v[30:31], v[108:109], s[40:41], v[8:9] op_sel_hi:[1,0,1]
	v_cvt_pk_fp8_f32 v20, v24, v25
	v_cvt_pk_fp8_f32 v21, v28, v29
	v_pk_fma_f32 v[22:23], v[130:131], s[40:41], v[14:15] op_sel_hi:[1,0,1]
	v_pk_fma_f32 v[24:25], v[114:115], s[40:41], v[14:15] op_sel_hi:[1,0,1]
	v_cvt_pk_fp8_f32 v20, v22, v23 op_sel:[0,0,1]
	v_cvt_pk_fp8_f32 v21, v26, v27 op_sel:[0,0,1]
	v_pk_fma_f32 v[26:27], v[112:113], s[40:41], v[10:11] op_sel_hi:[1,0,1]
	v_cvt_pk_fp8_f32 v22, v26, v27
	v_cvt_pk_fp8_f32 v23, v30, v31
	v_pk_fma_f32 v[28:29], v[110:111], s[40:41], v[12:13] op_sel_hi:[1,0,1]
	s_mov_b32 s2, 0x20000
	v_cvt_pk_fp8_f32 v22, v24, v25 op_sel:[0,0,1]
	v_cvt_pk_fp8_f32 v23, v28, v29 op_sel:[0,0,1]
	v_add_co_u32_e32 v24, vcc, s2, v18
	v_permlane16_swap_b32_e32 v20, v22
	v_permlane16_swap_b32_e32 v21, v23
	v_addc_co_u32_e32 v25, vcc, 0, v19, vcc
	global_store_dwordx4 v[24:25], v[20:23], off
	v_pk_fma_f32 v[26:27], v[120:121], s[40:41], v[0:1] op_sel_hi:[1,0,1]
	v_pk_fma_f32 v[30:31], v[116:117], s[40:41], v[4:5] op_sel_hi:[1,0,1]
	v_cvt_pk_fp8_f32 v20, v26, v27
	v_cvt_pk_fp8_f32 v21, v30, v31
	v_pk_fma_f32 v[22:23], v[122:123], s[40:41], v[2:3] op_sel_hi:[1,0,1]
	v_pk_fma_f32 v[28:29], v[118:119], s[40:41], v[6:7] op_sel_hi:[1,0,1]
	v_cvt_pk_fp8_f32 v20, v22, v23 op_sel:[0,0,1]
	v_cvt_pk_fp8_f32 v21, v28, v29 op_sel:[0,0,1]
	v_pk_fma_f32 v[28:29], v[104:105], s[40:41], v[0:1] op_sel_hi:[1,0,1]
	v_pk_fma_f32 v[32:33], v[100:101], s[40:41], v[4:5] op_sel_hi:[1,0,1]
	v_cvt_pk_fp8_f32 v22, v28, v29
	v_cvt_pk_fp8_f32 v23, v32, v33
	v_pk_fma_f32 v[26:27], v[106:107], s[40:41], v[2:3] op_sel_hi:[1,0,1]
	v_pk_fma_f32 v[30:31], v[102:103], s[40:41], v[6:7] op_sel_hi:[1,0,1]
	v_cvt_pk_fp8_f32 v22, v26, v27 op_sel:[0,0,1]
	v_cvt_pk_fp8_f32 v23, v30, v31 op_sel:[0,0,1]
	v_pk_fma_f32 v[28:29], v[84:85], s[40:41], v[8:9] op_sel_hi:[1,0,1]
	v_pk_fma_f32 v[8:9], v[68:69], s[40:41], v[8:9] op_sel_hi:[1,0,1]
	v_permlane16_swap_b32_e32 v20, v22
	v_permlane16_swap_b32_e32 v21, v23
	global_store_dwordx4 v[24:25], v[20:23], off offset:128
	v_pk_fma_f32 v[24:25], v[92:93], s[40:41], v[10:11] op_sel_hi:[1,0,1]
	v_pk_fma_f32 v[10:11], v[72:73], s[40:41], v[10:11] op_sel_hi:[1,0,1]
	v_cvt_pk_fp8_f32 v20, v24, v25
	v_pk_fma_f32 v[22:23], v[94:95], s[40:41], v[14:15] op_sel_hi:[1,0,1]
	v_cvt_pk_fp8_f32 v21, v28, v29
	v_cvt_pk_fp8_f32 v20, v22, v23 op_sel:[0,0,1]
	v_cvt_pk_fp8_f32 v22, v10, v11
	v_cvt_pk_fp8_f32 v23, v8, v9
	v_pk_fma_f32 v[26:27], v[86:87], s[40:41], v[12:13] op_sel_hi:[1,0,1]
	v_pk_fma_f32 v[14:15], v[74:75], s[40:41], v[14:15] op_sel_hi:[1,0,1]
	v_pk_fma_f32 v[12:13], v[70:71], s[40:41], v[12:13] op_sel_hi:[1,0,1]
	v_cvt_pk_fp8_f32 v21, v26, v27 op_sel:[0,0,1]
	v_cvt_pk_fp8_f32 v22, v14, v15 op_sel:[0,0,1]
	v_cvt_pk_fp8_f32 v23, v12, v13 op_sel:[0,0,1]
	v_pk_fma_f32 v[14:15], v[96:97], s[40:41], v[0:1] op_sel_hi:[1,0,1]
	v_cvt_pk_fp8_f32 v8, v14, v15
	s_mov_b32 s2, 0x28000
	v_add_co_u32_e32 v12, vcc, s2, v18
	v_permlane16_swap_b32_e32 v20, v22
	v_permlane16_swap_b32_e32 v21, v23
	v_addc_co_u32_e32 v13, vcc, 0, v19, vcc
	v_pk_fma_f32 v[10:11], v[98:99], s[40:41], v[2:3] op_sel_hi:[1,0,1]
	global_store_dwordx4 v[12:13], v[20:23], off
	v_cvt_pk_fp8_f32 v8, v10, v11 op_sel:[0,0,1]
	v_pk_fma_f32 v[20:21], v[88:89], s[40:41], v[4:5] op_sel_hi:[1,0,1]
	v_pk_fma_f32 v[0:1], v[80:81], s[40:41], v[0:1] op_sel_hi:[1,0,1]
	v_pk_fma_f32 v[4:5], v[76:77], s[40:41], v[4:5] op_sel_hi:[1,0,1]
	v_cvt_pk_fp8_f32 v9, v20, v21
	v_cvt_pk_fp8_f32 v10, v0, v1
	v_cvt_pk_fp8_f32 v11, v4, v5
	v_pk_fma_f32 v[18:19], v[90:91], s[40:41], v[6:7] op_sel_hi:[1,0,1]
	v_pk_fma_f32 v[2:3], v[82:83], s[40:41], v[2:3] op_sel_hi:[1,0,1]
	v_pk_fma_f32 v[6:7], v[78:79], s[40:41], v[6:7] op_sel_hi:[1,0,1]
	v_cvt_pk_fp8_f32 v9, v18, v19 op_sel:[0,0,1]
	v_cvt_pk_fp8_f32 v10, v2, v3 op_sel:[0,0,1]
	v_cvt_pk_fp8_f32 v11, v6, v7 op_sel:[0,0,1]
	s_mov_b64 s[2:3], -1
	s_and_b64 vcc, exec, s[42:43]
	v_permlane16_swap_b32_e32 v8, v10
	v_permlane16_swap_b32_e32 v9, v11
	global_store_dwordx4 v[12:13], v[8:11], off offset:128
	s_cbranch_vccnz .LBB0_1101
	s_andn2_b64 vcc, exec, s[44:45]
	s_and_b32 s90, s89, 1
	s_cbranch_vccnz .LBB0_1129
	s_lshl_b64 s[2:3], s[50:51], 12
	s_add_u32 s37, s74, s2
	s_addc_u32 s40, s75, s3
	s_lshl_b32 s2, s36, 8
	s_ashr_i32 s3, s2, 31
	s_lshl_b64 s[2:3], s[2:3], 2
	s_add_u32 s2, s37, s2
	s_addc_u32 s3, s40, s3
	s_lshl_b32 s37, s90, 10
	s_add_i32 s37, s37, 0
	s_add_i32 m0, s37, 0x21400
	s_nop 0
	global_load_lds_dwordx4 v232, s[2:3]
